# v144 plus accumulator zeroing folded into the hand-written P1 and P5 epilogues (compiler zero block skipped after an epilogue)
# speedup vs baseline: 1.0242x; 1.0044x over previous
; #define PG8_STAGE(bufoff, gbase, voff) do { _Pragma("unroll") for (int _i = 0; _i < 2; ++_i) \
;         __builtin_amdgcn_global_load_lds((const unsigned*)((const char*)(gbase) + (voff)[_i]), (PG8_LAS unsigned*)(lds + (bufoff) + ldsw + _i * 8192), 16, 0, 0); } while (0)
; #define PG8_LDA(dst, b, h) do { _Pragma("unroll") for (int m = 0; m < 4; ++m) _Pragma("unroll") for (int k = 0; k < 2; ++k) dst[m][k] = *(const PG8_LAS bf16x8*)(lds + PG8_SA(b, h) + aoff + m * 2048 + k * 1024); } while (0)
; #define PG8_LDB(dst, b, h) do { _Pragma("unroll") for (int n = 0; n < 2; ++n) _Pragma("unroll") for (int k = 0; k < 2; ++k) dst[n][k] = *(const PG8_LAS bf16x8*)(lds + PG8_SB(b, h) + boff + n * 2048 + k * 1024); } while (0)
; #define PG8_MMA(ai, bj, At, Bt) do { __builtin_amdgcn_s_setprio(1); _Pragma("unroll") for (int m = 0; m < 4; ++m) _Pragma("unroll") for (int n = 0; n < 2; ++n) _Pragma("unroll") for (int k = 0; k < 2; ++k) \
;         acc[ai][bj][m][n] = __builtin_amdgcn_mfma_f32_16x16x32_bf16(Bt[n][k], At[m][k], acc[ai][bj][m][n], 0, 0, 0); __builtin_amdgcn_s_setprio(0); } while (0)
; #define PG8_WAIT_V(n) asm volatile("s_waitcnt vmcnt(" #n ")" ::: "memory")
; template <class Epi, class Sched, bool ALIGN_EPI = false, bool SP2 = false>
; __device__ __forceinline__ void gemm_phase(PG8_LAS unsigned char* lds, const Gemm g, const Sched& S, const Epi& E) {
;     ...
;         for (int t = 0; t < nt; t += 2) {
;             const bool last = (t == nt - 2);
;             const char* a1 = cA + (size_t)(t + 1) * kstep;
;             const char* a2 = last ? nA : cA + (size_t)(t + 2) * kstep; const char* b2 = last ? nB : cB + (size_t)(t + 2) * kstep;
;             const char* a3 = a2 + kstep; const char* b3 = b2 + kstep;
;             if (last && has_next) S.a_ready(nxt);
;             if constexpr (SP2) {
;             PG8_LDB(B0, 0, 0); PG8_LDB(B1, 0, 1); PG8_SCHED; PG8_LDA(At, 0, 0); PG8_STAGE(PG8_SA(1, 1), a1 + hstep, voffA);
;             PG8_WAIT_V(8); PG8_WAIT_L(0); PG8_BAR; PG8_MMA(0, 0, At, B0); PG8_MMA(0, 1, At, B1); PG8_BAR; PG8_SCHED;
;     ...
; #pragma unroll
;         for (int a = 0; a < 2; ++a)
; #pragma unroll
;             for (int b = 0; b < 2; ++b)
; #pragma unroll
;                 for (int m = 0; m < 4; ++m)
; #pragma unroll
;                     for (int n = 0; n < 2; ++n) acc[a][b][m][n] = (f32x4){0.f, 0.f, 0.f, 0.f};
;         cur = nxt; cA = nA; cB = nB; ++ui;
.LBB0_123:
	s_ashr_i32 s25, s24, 31
	s_lshl_b64 s[8:9], s[24:25], 19
	s_add_u32 s26, s50, s8
	s_addc_u32 s27, s51, s9
	s_and_b64 s[8:9], s[0:1], exec
	s_cselect_b32 s3, s27, s79
	s_cselect_b32 s5, s26, s78
	s_ashr_i32 s23, s22, 31
	s_lshl_b64 s[8:9], s[22:23], 19
	s_add_u32 s54, s14, s8
	s_addc_u32 s55, s15, s9
	s_and_b64 s[8:9], s[0:1], exec
	s_cselect_b32 s7, s55, s81
	s_cselect_b32 s8, s54, s80
	s_add_u32 s78, s78, 0x40080
	s_addc_u32 s79, s79, 0
	s_add_u32 s9, s80, 0x100
	v_mov_b32_e32 v0, 0
	s_addc_u32 s10, s81, 0
	s_mov_b32 s11, -2
	s_cmp_lg_u32 s101, 0
	s_cbranch_scc1 .Lskipz_p1
	v_mov_b32_e32 v1, v0
	v_mov_b32_e32 v2, v0
	v_mov_b32_e32 v3, v0
	v_mov_b32_e32 v4, v0
	v_mov_b32_e32 v5, v0
	v_mov_b32_e32 v6, v0
	v_mov_b32_e32 v7, v0
	v_mov_b32_e32 v16, v0
	v_mov_b32_e32 v17, v0
	v_mov_b32_e32 v18, v0
	v_mov_b32_e32 v19, v0
	v_mov_b32_e32 v20, v0
	v_mov_b32_e32 v21, v0
	v_mov_b32_e32 v22, v0
	v_mov_b32_e32 v23, v0
	v_mov_b32_e32 v32, v0
	v_mov_b32_e32 v33, v0
	v_mov_b32_e32 v34, v0
	v_mov_b32_e32 v35, v0
	v_mov_b32_e32 v36, v0
	v_mov_b32_e32 v37, v0
	v_mov_b32_e32 v38, v0
	v_mov_b32_e32 v39, v0
	v_mov_b32_e32 v48, v0
	v_mov_b32_e32 v49, v0
	v_mov_b32_e32 v50, v0
	v_mov_b32_e32 v51, v0
	v_mov_b32_e32 v52, v0
	v_mov_b32_e32 v53, v0
	v_mov_b32_e32 v54, v0
	v_mov_b32_e32 v55, v0
	v_mov_b32_e32 v8, v0
	v_mov_b32_e32 v9, v0
	v_mov_b32_e32 v10, v0
	v_mov_b32_e32 v11, v0
	v_mov_b32_e32 v12, v0
	v_mov_b32_e32 v13, v0
	v_mov_b32_e32 v14, v0
	v_mov_b32_e32 v15, v0
	v_mov_b32_e32 v24, v0
	v_mov_b32_e32 v25, v0
	v_mov_b32_e32 v26, v0
	v_mov_b32_e32 v27, v0
	v_mov_b32_e32 v28, v0
	v_mov_b32_e32 v29, v0
	v_mov_b32_e32 v30, v0
	v_mov_b32_e32 v31, v0
	v_mov_b32_e32 v40, v0
	v_mov_b32_e32 v41, v0
	v_mov_b32_e32 v42, v0
	v_mov_b32_e32 v43, v0
	v_mov_b32_e32 v44, v0
	v_mov_b32_e32 v45, v0
	v_mov_b32_e32 v46, v0
	v_mov_b32_e32 v47, v0
	v_mov_b32_e32 v56, v0
	v_mov_b32_e32 v57, v0
	v_mov_b32_e32 v58, v0
	v_mov_b32_e32 v59, v0
	v_mov_b32_e32 v60, v0
	v_mov_b32_e32 v61, v0
	v_mov_b32_e32 v62, v0
	v_mov_b32_e32 v63, v0
	v_mov_b32_e32 v64, v0
	v_mov_b32_e32 v65, v0
	v_mov_b32_e32 v66, v0
	v_mov_b32_e32 v67, v0
	v_mov_b32_e32 v68, v0
	v_mov_b32_e32 v69, v0
	v_mov_b32_e32 v70, v0
	v_mov_b32_e32 v71, v0
	v_mov_b32_e32 v80, v0
	v_mov_b32_e32 v81, v0
	v_mov_b32_e32 v82, v0
	v_mov_b32_e32 v83, v0
	v_mov_b32_e32 v84, v0
	v_mov_b32_e32 v85, v0
	v_mov_b32_e32 v86, v0
	v_mov_b32_e32 v87, v0
	v_mov_b32_e32 v96, v0
	v_mov_b32_e32 v97, v0
	v_mov_b32_e32 v98, v0
	v_mov_b32_e32 v99, v0
	v_mov_b32_e32 v100, v0
	v_mov_b32_e32 v101, v0
	v_mov_b32_e32 v102, v0
	v_mov_b32_e32 v103, v0
	v_mov_b32_e32 v112, v0
	v_mov_b32_e32 v113, v0
	v_mov_b32_e32 v114, v0
	v_mov_b32_e32 v115, v0
	v_mov_b32_e32 v116, v0
	v_mov_b32_e32 v117, v0
	v_mov_b32_e32 v118, v0
	v_mov_b32_e32 v119, v0
	v_mov_b32_e32 v72, v0
	v_mov_b32_e32 v73, v0
	v_mov_b32_e32 v74, v0
	v_mov_b32_e32 v75, v0
	v_mov_b32_e32 v76, v0
	v_mov_b32_e32 v77, v0
	v_mov_b32_e32 v78, v0
	v_mov_b32_e32 v79, v0
	v_mov_b32_e32 v88, v0
	v_mov_b32_e32 v89, v0
	v_mov_b32_e32 v90, v0
	v_mov_b32_e32 v91, v0
	v_mov_b32_e32 v92, v0
	v_mov_b32_e32 v93, v0
	v_mov_b32_e32 v94, v0
	v_mov_b32_e32 v95, v0
	v_mov_b32_e32 v104, v0
	v_mov_b32_e32 v105, v0
	v_mov_b32_e32 v106, v0
	v_mov_b32_e32 v107, v0
	v_mov_b32_e32 v108, v0
	v_mov_b32_e32 v109, v0
	v_mov_b32_e32 v110, v0
	v_mov_b32_e32 v111, v0
	v_mov_b32_e32 v120, v0
	v_mov_b32_e32 v121, v0
	v_mov_b32_e32 v122, v0
	v_mov_b32_e32 v123, v0
	v_mov_b32_e32 v124, v0
	v_mov_b32_e32 v125, v0
	v_mov_b32_e32 v126, v0
	v_mov_b32_e32 v127, v0
.Lskipz_p1:
.LBB0_124:
	ds_read_b128 v[146:149], v157
	ds_read_b128 v[150:153], v157 offset:1024
	ds_read_b128 v[160:163], v157 offset:2048
	ds_read_b128 v[164:167], v157 offset:3072
	ds_read_b128 v[168:171], v158
	ds_read_b128 v[172:175], v158 offset:1024
	ds_read_b128 v[176:179], v158 offset:2048
	ds_read_b128 v[180:183], v158 offset:3072
	s_add_u32 s12, s78, 0xfffc0080
	s_addc_u32 s13, s79, -1
	s_cmp_eq_u32 s11, 12
	s_cselect_b32 s83, s3, s13
	s_cselect_b32 s82, s5, s12
	s_cselect_b32 s81, s7, s10
	s_cselect_b32 s80, s8, s9
	v_lshl_add_u64 v[218:219], s[78:79], 0, v[138:139]
	s_add_i32 m0, s87, 0xc000
	ds_read_b128 v[184:187], v159
	ds_read_b128 v[188:191], v159 offset:1024
	ds_read_b128 v[192:195], v159 offset:2048
	ds_read_b128 v[196:199], v159 offset:3072
	ds_read_b128 v[200:203], v159 offset:4096
	ds_read_b128 v[206:209], v159 offset:5120
	ds_read_b128 v[210:213], v159 offset:6144
	ds_read_b128 v[214:217], v159 offset:7168
	s_cmp_lg_u32 s101, 0
	s_cbranch_scc1 .Lgr_p1_alt1
	global_load_lds_dwordx4 v[218:219], off
	v_lshl_add_u64 v[218:219], s[78:79], 0, v[140:141]
	s_add_i32 m0, s87, 0xe000
	s_nop 0
	global_load_lds_dwordx4 v[218:219], off
	s_waitcnt vmcnt(8)
	s_branch .Lgr_p1_join1

; __device__ __forceinline__ u32x4 pack8(const float (&f)[8]) { u32x4 w; w.x = cvt_pk_bf16(f[0], f[1]); w.y = cvt_pk_bf16(f[2], f[3]); w.z = cvt_pk_bf16(f[4], f[5]); w.w = cvt_pk_bf16(f[6], f[7]); return w; }
; __device__ __forceinline__ float sigm(float x) { return __builtin_amdgcn_rcpf(1.f + __builtin_amdgcn_exp2f(-1.4426950408889634f * x)); }
;     __device__ __forceinline__ void operator()(const f32x4 (&acc)[2][2][4][2], const Unit& u, int wr, int wc, int fr, int fq) const {
;         const int pn = u.pn; const int row0 = u.pm * BM + wr * 64 + fr;
;         size_t off; int ldc = 1024, colt, act = 0;
;         if (pn < 16) { off = WS_QK + (size_t)(pn >> 2) * (64 * MiB); colt = (pn & 3) * 256; if ((pn >> 2) == 2) act = 2; }
;         else if (pn < 18) { off = WS_SKV; ldc = 512; colt = (pn - 16) * 256; }
;         else if (pn < 22) { off = WS_GA; colt = (pn - 18) * 256; act = 1; }
;         else { off = WS_GB; colt = (pn - 22) * 256; act = 1; }
;         bf16_t* base = (bf16_t*)(ws + off);
;         const int col0 = colt + wc * 32 + 8 * fq;
; #pragma unroll
;         for (int ai = 0; ai < 2; ++ai)
; #pragma unroll
;             for (int m = 0; m < 4; ++m) { bf16_t* rowp = base + (size_t)(row0 + ai * HALF + m * 16) * ldc + col0;
; #pragma unroll
;                 for (int bj = 0; bj < 2; ++bj) { const f32x4 v0 = acc[ai][bj][m][0], v1 = acc[ai][bj][m][1];
;                     float f[8] = {v0[0], v0[1], v0[2], v0[3], v1[0], v1[1], v1[2], v1[3]};
;                     if (act == 1) {
; #pragma unroll
;                         for (int e = 0; e < 8; ++e) f[e] = sigm(f[e]);
;                     } else if (act == 2) {
; #pragma unroll
;                         for (int e = 0; e < 8; ++e) f[e] = f[e] * sigm(f[e]);
;                     }
;                     __builtin_nontemporal_store(pack8(f), (u32x4*)(rowp + bj * HALF)); } }
; template <class Epi, class Sched, bool ALIGN_EPI = false, bool SP2 = false>
; __device__ __forceinline__ void gemm_phase(PG8_LAS unsigned char* lds, const Gemm g, const Sched& S, const Epi& E) {
;     ...
; #pragma unroll
;         for (int a = 0; a < 2; ++a)
; #pragma unroll
;             for (int b = 0; b < 2; ++b)
; #pragma unroll
;                 for (int m = 0; m < 4; ++m)
; #pragma unroll
;                     for (int n = 0; n < 2; ++n) acc[a][b][m][n] = (f32x4){0.f, 0.f, 0.f, 0.f};
;         cur = nxt; cA = nA; cB = nB; ++ui;
.Lp1_plain:
	v_lshl_add_u32 v160, s6, 8, v154
	v_add_u32_e32 v136, s3, v156
	s_add_u32 s98, s68, s80
	s_addc_u32 s99, s69, s81
	s_lshl_b32 s100, s78, 1
	v_mul_lo_u32 v160, v160, s100
	s_lshl_b32 s100, s78, 5
	v_lshl_add_u32 v160, v136, 1, v160
	v_cvt_pk_bf16_f32 v124, v124, v125
	v_cvt_pk_bf16_f32 v125, v126, v127
	v_cvt_pk_bf16_f32 v126, v120, v121
	v_cvt_pk_bf16_f32 v127, v122, v123
	ds_write_b128 v228, v[124:127]
	ds_read_b128 v[120:123], v229
	v_cvt_pk_bf16_f32 v116, v116, v117
	v_cvt_pk_bf16_f32 v117, v118, v119
	v_cvt_pk_bf16_f32 v118, v112, v113
	v_cvt_pk_bf16_f32 v119, v114, v115
	ds_write_b128 v228, v[116:119]
	ds_read_b128 v[112:115], v229
	v_cvt_pk_bf16_f32 v108, v108, v109
	v_cvt_pk_bf16_f32 v109, v110, v111
	v_cvt_pk_bf16_f32 v110, v104, v105
	v_cvt_pk_bf16_f32 v111, v106, v107
	ds_write_b128 v228, v[108:111]
	ds_read_b128 v[104:107], v229
	v_cvt_pk_bf16_f32 v100, v100, v101
	v_cvt_pk_bf16_f32 v101, v102, v103
	v_cvt_pk_bf16_f32 v102, v96, v97
	v_cvt_pk_bf16_f32 v103, v98, v99
	ds_write_b128 v228, v[100:103]
	ds_read_b128 v[96:99], v229
	v_pk_mov_b32 v[124:125], 0, 0
	v_pk_mov_b32 v[126:127], 0, 0
	v_pk_mov_b32 v[116:117], 0, 0
	v_pk_mov_b32 v[118:119], 0, 0
	v_pk_mov_b32 v[108:109], 0, 0
	v_pk_mov_b32 v[110:111], 0, 0
	v_pk_mov_b32 v[100:101], 0, 0
	v_pk_mov_b32 v[102:103], 0, 0
	s_waitcnt lgkmcnt(6)
	global_store_dwordx4 v160, v[120:123], s[98:99] nt
	s_waitcnt lgkmcnt(4)
	global_store_dwordx4 v160, v[112:115], s[98:99] offset:256 nt
	v_add_u32_e32 v160, s100, v160
	s_waitcnt lgkmcnt(2)
	global_store_dwordx4 v160, v[104:107], s[98:99] nt
	s_waitcnt lgkmcnt(0)
	global_store_dwordx4 v160, v[96:99], s[98:99] offset:256 nt
	v_pk_mov_b32 v[120:121], 0, 0
	v_pk_mov_b32 v[122:123], 0, 0
	v_pk_mov_b32 v[112:113], 0, 0
	v_pk_mov_b32 v[114:115], 0, 0
	v_pk_mov_b32 v[104:105], 0, 0
	v_pk_mov_b32 v[106:107], 0, 0
	v_pk_mov_b32 v[96:97], 0, 0
	v_pk_mov_b32 v[98:99], 0, 0
	v_cvt_pk_bf16_f32 v92, v92, v93
	v_cvt_pk_bf16_f32 v93, v94, v95
	v_cvt_pk_bf16_f32 v94, v88, v89
	v_cvt_pk_bf16_f32 v95, v90, v91
	ds_write_b128 v228, v[92:95]
	ds_read_b128 v[88:91], v229
	v_cvt_pk_bf16_f32 v84, v84, v85
	v_cvt_pk_bf16_f32 v85, v86, v87
	v_cvt_pk_bf16_f32 v86, v80, v81
	v_cvt_pk_bf16_f32 v87, v82, v83
	ds_write_b128 v228, v[84:87]
	ds_read_b128 v[80:83], v229
	v_cvt_pk_bf16_f32 v76, v76, v77
	v_cvt_pk_bf16_f32 v77, v78, v79
	v_cvt_pk_bf16_f32 v78, v72, v73
	v_cvt_pk_bf16_f32 v79, v74, v75
	ds_write_b128 v228, v[76:79]
	ds_read_b128 v[72:75], v229
	v_cvt_pk_bf16_f32 v68, v68, v69
	v_cvt_pk_bf16_f32 v69, v70, v71
	v_cvt_pk_bf16_f32 v70, v64, v65
	v_cvt_pk_bf16_f32 v71, v66, v67
	ds_write_b128 v228, v[68:71]
	ds_read_b128 v[64:67], v229
	v_pk_mov_b32 v[92:93], 0, 0
	v_pk_mov_b32 v[94:95], 0, 0
	v_pk_mov_b32 v[84:85], 0, 0
	v_pk_mov_b32 v[86:87], 0, 0
	v_pk_mov_b32 v[76:77], 0, 0
	v_pk_mov_b32 v[78:79], 0, 0
	v_pk_mov_b32 v[68:69], 0, 0
	v_pk_mov_b32 v[70:71], 0, 0
	v_add_u32_e32 v160, s100, v160
	s_waitcnt lgkmcnt(6)
	global_store_dwordx4 v160, v[88:91], s[98:99] nt
	s_waitcnt lgkmcnt(4)
	global_store_dwordx4 v160, v[80:83], s[98:99] offset:256 nt
	v_add_u32_e32 v160, s100, v160
	s_waitcnt lgkmcnt(2)
	global_store_dwordx4 v160, v[72:75], s[98:99] nt
	s_waitcnt lgkmcnt(0)
	global_store_dwordx4 v160, v[64:67], s[98:99] offset:256 nt
	v_pk_mov_b32 v[88:89], 0, 0
	v_pk_mov_b32 v[90:91], 0, 0
	v_pk_mov_b32 v[80:81], 0, 0
	v_pk_mov_b32 v[82:83], 0, 0
	v_pk_mov_b32 v[72:73], 0, 0
	v_pk_mov_b32 v[74:75], 0, 0
	v_pk_mov_b32 v[64:65], 0, 0
	v_pk_mov_b32 v[66:67], 0, 0
	v_cvt_pk_bf16_f32 v60, v60, v61
	v_cvt_pk_bf16_f32 v61, v62, v63
	v_cvt_pk_bf16_f32 v62, v56, v57
	v_cvt_pk_bf16_f32 v63, v58, v59
	ds_write_b128 v228, v[60:63]
	ds_read_b128 v[56:59], v229
	v_cvt_pk_bf16_f32 v52, v52, v53
	v_cvt_pk_bf16_f32 v53, v54, v55
	v_cvt_pk_bf16_f32 v54, v48, v49
	v_cvt_pk_bf16_f32 v55, v50, v51
	ds_write_b128 v228, v[52:55]
	ds_read_b128 v[48:51], v229
	v_cvt_pk_bf16_f32 v44, v44, v45
	v_cvt_pk_bf16_f32 v45, v46, v47
	v_cvt_pk_bf16_f32 v46, v40, v41
	v_cvt_pk_bf16_f32 v47, v42, v43
	ds_write_b128 v228, v[44:47]
	ds_read_b128 v[40:43], v229
	v_cvt_pk_bf16_f32 v36, v36, v37
	v_cvt_pk_bf16_f32 v37, v38, v39
	v_cvt_pk_bf16_f32 v38, v32, v33
	v_cvt_pk_bf16_f32 v39, v34, v35
	ds_write_b128 v228, v[36:39]
	ds_read_b128 v[32:35], v229
	v_pk_mov_b32 v[60:61], 0, 0
	v_pk_mov_b32 v[62:63], 0, 0
	v_pk_mov_b32 v[52:53], 0, 0
	v_pk_mov_b32 v[54:55], 0, 0
	v_pk_mov_b32 v[44:45], 0, 0
	v_pk_mov_b32 v[46:47], 0, 0
	v_pk_mov_b32 v[36:37], 0, 0
	v_pk_mov_b32 v[38:39], 0, 0
	v_mad_u32_u24 v160, s100, 5, v160
	s_waitcnt lgkmcnt(6)
	global_store_dwordx4 v160, v[56:59], s[98:99] nt
	s_waitcnt lgkmcnt(4)
	global_store_dwordx4 v160, v[48:51], s[98:99] offset:256 nt
	v_add_u32_e32 v160, s100, v160
	s_waitcnt lgkmcnt(2)
	global_store_dwordx4 v160, v[40:43], s[98:99] nt
	s_waitcnt lgkmcnt(0)
	global_store_dwordx4 v160, v[32:35], s[98:99] offset:256 nt
	v_pk_mov_b32 v[56:57], 0, 0
	v_pk_mov_b32 v[58:59], 0, 0
	v_pk_mov_b32 v[48:49], 0, 0
	v_pk_mov_b32 v[50:51], 0, 0
	v_pk_mov_b32 v[40:41], 0, 0
	v_pk_mov_b32 v[42:43], 0, 0
	v_pk_mov_b32 v[32:33], 0, 0
	v_pk_mov_b32 v[34:35], 0, 0
	v_cvt_pk_bf16_f32 v28, v28, v29
	v_cvt_pk_bf16_f32 v29, v30, v31
	v_cvt_pk_bf16_f32 v30, v24, v25
	v_cvt_pk_bf16_f32 v31, v26, v27
	ds_write_b128 v228, v[28:31]
	ds_read_b128 v[24:27], v229
	v_cvt_pk_bf16_f32 v20, v20, v21
	v_cvt_pk_bf16_f32 v21, v22, v23
	v_cvt_pk_bf16_f32 v22, v16, v17
	v_cvt_pk_bf16_f32 v23, v18, v19
	ds_write_b128 v228, v[20:23]
	ds_read_b128 v[16:19], v229
	v_cvt_pk_bf16_f32 v12, v12, v13
	v_cvt_pk_bf16_f32 v13, v14, v15
	v_cvt_pk_bf16_f32 v14, v8, v9
	v_cvt_pk_bf16_f32 v15, v10, v11
	ds_write_b128 v228, v[12:15]
	ds_read_b128 v[8:11], v229
	v_cvt_pk_bf16_f32 v4, v4, v5
	v_cvt_pk_bf16_f32 v5, v6, v7
	v_cvt_pk_bf16_f32 v6, v0, v1
	v_cvt_pk_bf16_f32 v7, v2, v3
	ds_write_b128 v228, v[4:7]
	ds_read_b128 v[0:3], v229
	v_pk_mov_b32 v[28:29], 0, 0
	v_pk_mov_b32 v[30:31], 0, 0
	v_pk_mov_b32 v[20:21], 0, 0
	v_pk_mov_b32 v[22:23], 0, 0
	v_pk_mov_b32 v[12:13], 0, 0
	v_pk_mov_b32 v[14:15], 0, 0
	v_pk_mov_b32 v[4:5], 0, 0
	v_pk_mov_b32 v[6:7], 0, 0
	v_add_u32_e32 v160, s100, v160
	s_waitcnt lgkmcnt(6)
	global_store_dwordx4 v160, v[24:27], s[98:99] nt
	s_waitcnt lgkmcnt(4)
	global_store_dwordx4 v160, v[16:19], s[98:99] offset:256 nt
	v_add_u32_e32 v160, s100, v160
	s_waitcnt lgkmcnt(2)
	global_store_dwordx4 v160, v[8:11], s[98:99] nt
	s_waitcnt lgkmcnt(0)
	global_store_dwordx4 v160, v[0:3], s[98:99] offset:256 nt
	v_pk_mov_b32 v[24:25], 0, 0
	v_pk_mov_b32 v[26:27], 0, 0
	v_pk_mov_b32 v[16:17], 0, 0
	v_pk_mov_b32 v[18:19], 0, 0
	v_pk_mov_b32 v[8:9], 0, 0
	v_pk_mov_b32 v[10:11], 0, 0
	v_pk_mov_b32 v[0:1], 0, 0
	v_pk_mov_b32 v[2:3], 0, 0
	s_andn2_b64 vcc, exec, s[0:1]
	s_mov_b64 s[0:1], -1
	s_branch .Lp1_tail
; __device__ __forceinline__ u32x4 pack8(const float (&f)[8]) { u32x4 w; w.x = cvt_pk_bf16(f[0], f[1]); w.y = cvt_pk_bf16(f[2], f[3]); w.z = cvt_pk_bf16(f[4], f[5]); w.w = cvt_pk_bf16(f[6], f[7]); return w; }
; __device__ __forceinline__ float sigm(float x) { return __builtin_amdgcn_rcpf(1.f + __builtin_amdgcn_exp2f(-1.4426950408889634f * x)); }
;     __device__ __forceinline__ void operator()(const f32x4 (&acc)[2][2][4][2], const Unit& u, int wr, int wc, int fr, int fq) const {
;     ...
;                     } else if (act == 2) {
; #pragma unroll
;                         for (int e = 0; e < 8; ++e) f[e] = f[e] * sigm(f[e]);
;                     }
;                     __builtin_nontemporal_store(pack8(f), (u32x4*)(rowp + bj * HALF)); } }
; template <class Epi, class Sched, bool ALIGN_EPI = false, bool SP2 = false>
; __device__ __forceinline__ void gemm_phase(PG8_LAS unsigned char* lds, const Gemm g, const Sched& S, const Epi& E) {
;     ...
; #pragma unroll
;         for (int a = 0; a < 2; ++a)
; #pragma unroll
;             for (int b = 0; b < 2; ++b)
; #pragma unroll
;                 for (int m = 0; m < 4; ++m)
; #pragma unroll
;                     for (int n = 0; n < 2; ++n) acc[a][b][m][n] = (f32x4){0.f, 0.f, 0.f, 0.f};
;         cur = nxt; cA = nA; cB = nB; ++ui;
.Lp1_silu:
	v_lshl_add_u32 v160, s6, 8, v154
	v_add_u32_e32 v136, s3, v156
	s_add_u32 s98, s68, s80
	s_addc_u32 s99, s69, s81
	s_lshl_b32 s100, s78, 1
	v_mul_lo_u32 v160, v160, s100
	s_lshl_b32 s100, s78, 5
	v_lshl_add_u32 v160, v136, 1, v160
	v_mov_b32_e32 v230, 0xbfb8aa3b
	v_mov_b32_e32 v231, 0xbfb8aa3b
	v_mov_b32_e32 v232, 1.0
	v_mov_b32_e32 v233, 1.0
	v_pk_mul_f32 v[234:235], v[124:125], v[230:231]
	v_pk_mul_f32 v[236:237], v[126:127], v[230:231]
	v_pk_mul_f32 v[238:239], v[120:121], v[230:231]
	v_pk_mul_f32 v[240:241], v[122:123], v[230:231]
	v_exp_f32_e32 v234, v234
	v_exp_f32_e32 v235, v235
	v_exp_f32_e32 v236, v236
	v_exp_f32_e32 v237, v237
	v_exp_f32_e32 v238, v238
	v_exp_f32_e32 v239, v239
	v_exp_f32_e32 v240, v240
	v_exp_f32_e32 v241, v241
	v_pk_add_f32 v[234:235], v[234:235], v[232:233]
	v_pk_add_f32 v[236:237], v[236:237], v[232:233]
	v_pk_add_f32 v[238:239], v[238:239], v[232:233]
	v_pk_add_f32 v[240:241], v[240:241], v[232:233]
	v_rcp_f32_e32 v234, v234
	v_rcp_f32_e32 v235, v235
	v_rcp_f32_e32 v236, v236
	v_rcp_f32_e32 v237, v237
	v_rcp_f32_e32 v238, v238
	v_rcp_f32_e32 v239, v239
	v_rcp_f32_e32 v240, v240
	v_rcp_f32_e32 v241, v241
	v_pk_mul_f32 v[234:235], v[124:125], v[234:235]
	v_pk_mul_f32 v[236:237], v[126:127], v[236:237]
	v_pk_mul_f32 v[238:239], v[120:121], v[238:239]
	v_pk_mul_f32 v[240:241], v[122:123], v[240:241]
	v_cvt_pk_bf16_f32 v124, v234, v235
	v_cvt_pk_bf16_f32 v125, v236, v237
	v_cvt_pk_bf16_f32 v126, v238, v239
	v_cvt_pk_bf16_f32 v127, v240, v241
	ds_write_b128 v228, v[124:127]
	ds_read_b128 v[120:123], v229
	v_pk_mul_f32 v[234:235], v[116:117], v[230:231]
	v_pk_mul_f32 v[236:237], v[118:119], v[230:231]
	v_pk_mul_f32 v[238:239], v[112:113], v[230:231]
	v_pk_mul_f32 v[240:241], v[114:115], v[230:231]
	v_exp_f32_e32 v234, v234
	v_exp_f32_e32 v235, v235
	v_exp_f32_e32 v236, v236
	v_exp_f32_e32 v237, v237
	v_exp_f32_e32 v238, v238
	v_exp_f32_e32 v239, v239
	v_exp_f32_e32 v240, v240
	v_exp_f32_e32 v241, v241
	v_pk_add_f32 v[234:235], v[234:235], v[232:233]
	v_pk_add_f32 v[236:237], v[236:237], v[232:233]
	v_pk_add_f32 v[238:239], v[238:239], v[232:233]
	v_pk_add_f32 v[240:241], v[240:241], v[232:233]
	v_rcp_f32_e32 v234, v234
	v_rcp_f32_e32 v235, v235
	v_rcp_f32_e32 v236, v236
	v_rcp_f32_e32 v237, v237
	v_rcp_f32_e32 v238, v238
	v_rcp_f32_e32 v239, v239
	v_rcp_f32_e32 v240, v240
	v_rcp_f32_e32 v241, v241
	v_pk_mul_f32 v[234:235], v[116:117], v[234:235]
	v_pk_mul_f32 v[236:237], v[118:119], v[236:237]
	v_pk_mul_f32 v[238:239], v[112:113], v[238:239]
	v_pk_mul_f32 v[240:241], v[114:115], v[240:241]
	v_cvt_pk_bf16_f32 v116, v234, v235
	v_cvt_pk_bf16_f32 v117, v236, v237
	v_cvt_pk_bf16_f32 v118, v238, v239
	v_cvt_pk_bf16_f32 v119, v240, v241
	ds_write_b128 v228, v[116:119]
	ds_read_b128 v[112:115], v229
	v_pk_mul_f32 v[234:235], v[108:109], v[230:231]
	v_pk_mul_f32 v[236:237], v[110:111], v[230:231]
	v_pk_mul_f32 v[238:239], v[104:105], v[230:231]
	v_pk_mul_f32 v[240:241], v[106:107], v[230:231]
	v_exp_f32_e32 v234, v234
	v_exp_f32_e32 v235, v235
	v_exp_f32_e32 v236, v236
	v_exp_f32_e32 v237, v237
	v_exp_f32_e32 v238, v238
	v_exp_f32_e32 v239, v239
	v_exp_f32_e32 v240, v240
	v_exp_f32_e32 v241, v241
	v_pk_add_f32 v[234:235], v[234:235], v[232:233]
	v_pk_add_f32 v[236:237], v[236:237], v[232:233]
	v_pk_add_f32 v[238:239], v[238:239], v[232:233]
	v_pk_add_f32 v[240:241], v[240:241], v[232:233]
	v_rcp_f32_e32 v234, v234
	v_rcp_f32_e32 v235, v235
	v_rcp_f32_e32 v236, v236
	v_rcp_f32_e32 v237, v237
	v_rcp_f32_e32 v238, v238
	v_rcp_f32_e32 v239, v239
	v_rcp_f32_e32 v240, v240
	v_rcp_f32_e32 v241, v241
	v_pk_mul_f32 v[234:235], v[108:109], v[234:235]
	v_pk_mul_f32 v[236:237], v[110:111], v[236:237]
	v_pk_mul_f32 v[238:239], v[104:105], v[238:239]
	v_pk_mul_f32 v[240:241], v[106:107], v[240:241]
	v_cvt_pk_bf16_f32 v108, v234, v235
	v_cvt_pk_bf16_f32 v109, v236, v237
	v_cvt_pk_bf16_f32 v110, v238, v239
	v_cvt_pk_bf16_f32 v111, v240, v241
	ds_write_b128 v228, v[108:111]
	ds_read_b128 v[104:107], v229
	v_pk_mul_f32 v[234:235], v[100:101], v[230:231]
	v_pk_mul_f32 v[236:237], v[102:103], v[230:231]
	v_pk_mul_f32 v[238:239], v[96:97], v[230:231]
	v_pk_mul_f32 v[240:241], v[98:99], v[230:231]
	v_exp_f32_e32 v234, v234
	v_exp_f32_e32 v235, v235
	v_exp_f32_e32 v236, v236
	v_exp_f32_e32 v237, v237
	v_exp_f32_e32 v238, v238
	v_exp_f32_e32 v239, v239
	v_exp_f32_e32 v240, v240
	v_exp_f32_e32 v241, v241
	v_pk_add_f32 v[234:235], v[234:235], v[232:233]
	v_pk_add_f32 v[236:237], v[236:237], v[232:233]
	v_pk_add_f32 v[238:239], v[238:239], v[232:233]
	v_pk_add_f32 v[240:241], v[240:241], v[232:233]
	v_rcp_f32_e32 v234, v234
	v_rcp_f32_e32 v235, v235
	v_rcp_f32_e32 v236, v236
	v_rcp_f32_e32 v237, v237
	v_rcp_f32_e32 v238, v238
	v_rcp_f32_e32 v239, v239
	v_rcp_f32_e32 v240, v240
	v_rcp_f32_e32 v241, v241
	v_pk_mul_f32 v[234:235], v[100:101], v[234:235]
	v_pk_mul_f32 v[236:237], v[102:103], v[236:237]
	v_pk_mul_f32 v[238:239], v[96:97], v[238:239]
	v_pk_mul_f32 v[240:241], v[98:99], v[240:241]
	v_cvt_pk_bf16_f32 v100, v234, v235
	v_cvt_pk_bf16_f32 v101, v236, v237
	v_cvt_pk_bf16_f32 v102, v238, v239
	v_cvt_pk_bf16_f32 v103, v240, v241
	ds_write_b128 v228, v[100:103]
	ds_read_b128 v[96:99], v229
	v_pk_mov_b32 v[124:125], 0, 0
	v_pk_mov_b32 v[126:127], 0, 0
	v_pk_mov_b32 v[116:117], 0, 0
	v_pk_mov_b32 v[118:119], 0, 0
	v_pk_mov_b32 v[108:109], 0, 0
	v_pk_mov_b32 v[110:111], 0, 0
	v_pk_mov_b32 v[100:101], 0, 0
	v_pk_mov_b32 v[102:103], 0, 0
	s_waitcnt lgkmcnt(6)
	global_store_dwordx4 v160, v[120:123], s[98:99] nt
	s_waitcnt lgkmcnt(4)
	global_store_dwordx4 v160, v[112:115], s[98:99] offset:256 nt
	v_add_u32_e32 v160, s100, v160
	s_waitcnt lgkmcnt(2)
; __device__ __forceinline__ u32x4 pack8(const float (&f)[8]) { u32x4 w; w.x = cvt_pk_bf16(f[0], f[1]); w.y = cvt_pk_bf16(f[2], f[3]); w.z = cvt_pk_bf16(f[4], f[5]); w.w = cvt_pk_bf16(f[6], f[7]); return w; }
; __device__ __forceinline__ float sigm(float x) { return __builtin_amdgcn_rcpf(1.f + __builtin_amdgcn_exp2f(-1.4426950408889634f * x)); }
;     __device__ __forceinline__ void operator()(const f32x4 (&acc)[2][2][4][2], const Unit& u, int wr, int wc, int fr, int fq) const {
;     ...
;                     } else if (act == 2) {
; #pragma unroll
;                         for (int e = 0; e < 8; ++e) f[e] = f[e] * sigm(f[e]);
;                     }
;                     __builtin_nontemporal_store(pack8(f), (u32x4*)(rowp + bj * HALF)); } }
; template <class Epi, class Sched, bool ALIGN_EPI = false, bool SP2 = false>
; __device__ __forceinline__ void gemm_phase(PG8_LAS unsigned char* lds, const Gemm g, const Sched& S, const Epi& E) {
;     ...
; #pragma unroll
;         for (int a = 0; a < 2; ++a)
; #pragma unroll
;             for (int b = 0; b < 2; ++b)
; #pragma unroll
;                 for (int m = 0; m < 4; ++m)
; #pragma unroll
;                     for (int n = 0; n < 2; ++n) acc[a][b][m][n] = (f32x4){0.f, 0.f, 0.f, 0.f};
;         cur = nxt; cA = nA; cB = nB; ++ui;
	global_store_dwordx4 v160, v[104:107], s[98:99] nt
	s_waitcnt lgkmcnt(0)
	global_store_dwordx4 v160, v[96:99], s[98:99] offset:256 nt
	v_pk_mov_b32 v[120:121], 0, 0
	v_pk_mov_b32 v[122:123], 0, 0
	v_pk_mov_b32 v[112:113], 0, 0
	v_pk_mov_b32 v[114:115], 0, 0
	v_pk_mov_b32 v[104:105], 0, 0
	v_pk_mov_b32 v[106:107], 0, 0
	v_pk_mov_b32 v[96:97], 0, 0
	v_pk_mov_b32 v[98:99], 0, 0
	v_pk_mul_f32 v[234:235], v[92:93], v[230:231]
	v_pk_mul_f32 v[236:237], v[94:95], v[230:231]
	v_pk_mul_f32 v[238:239], v[88:89], v[230:231]
	v_pk_mul_f32 v[240:241], v[90:91], v[230:231]
	v_exp_f32_e32 v234, v234
	v_exp_f32_e32 v235, v235
	v_exp_f32_e32 v236, v236
	v_exp_f32_e32 v237, v237
	v_exp_f32_e32 v238, v238
	v_exp_f32_e32 v239, v239
	v_exp_f32_e32 v240, v240
	v_exp_f32_e32 v241, v241
	v_pk_add_f32 v[234:235], v[234:235], v[232:233]
	v_pk_add_f32 v[236:237], v[236:237], v[232:233]
	v_pk_add_f32 v[238:239], v[238:239], v[232:233]
	v_pk_add_f32 v[240:241], v[240:241], v[232:233]
	v_rcp_f32_e32 v234, v234
	v_rcp_f32_e32 v235, v235
	v_rcp_f32_e32 v236, v236
	v_rcp_f32_e32 v237, v237
	v_rcp_f32_e32 v238, v238
	v_rcp_f32_e32 v239, v239
	v_rcp_f32_e32 v240, v240
	v_rcp_f32_e32 v241, v241
	v_pk_mul_f32 v[234:235], v[92:93], v[234:235]
	v_pk_mul_f32 v[236:237], v[94:95], v[236:237]
	v_pk_mul_f32 v[238:239], v[88:89], v[238:239]
	v_pk_mul_f32 v[240:241], v[90:91], v[240:241]
	v_cvt_pk_bf16_f32 v92, v234, v235
	v_cvt_pk_bf16_f32 v93, v236, v237
	v_cvt_pk_bf16_f32 v94, v238, v239
	v_cvt_pk_bf16_f32 v95, v240, v241
	ds_write_b128 v228, v[92:95]
	ds_read_b128 v[88:91], v229
	v_pk_mul_f32 v[234:235], v[84:85], v[230:231]
	v_pk_mul_f32 v[236:237], v[86:87], v[230:231]
	v_pk_mul_f32 v[238:239], v[80:81], v[230:231]
	v_pk_mul_f32 v[240:241], v[82:83], v[230:231]
	v_exp_f32_e32 v234, v234
	v_exp_f32_e32 v235, v235
	v_exp_f32_e32 v236, v236
	v_exp_f32_e32 v237, v237
	v_exp_f32_e32 v238, v238
	v_exp_f32_e32 v239, v239
	v_exp_f32_e32 v240, v240
	v_exp_f32_e32 v241, v241
	v_pk_add_f32 v[234:235], v[234:235], v[232:233]
	v_pk_add_f32 v[236:237], v[236:237], v[232:233]
	v_pk_add_f32 v[238:239], v[238:239], v[232:233]
	v_pk_add_f32 v[240:241], v[240:241], v[232:233]
	v_rcp_f32_e32 v234, v234
	v_rcp_f32_e32 v235, v235
	v_rcp_f32_e32 v236, v236
	v_rcp_f32_e32 v237, v237
	v_rcp_f32_e32 v238, v238
	v_rcp_f32_e32 v239, v239
	v_rcp_f32_e32 v240, v240
	v_rcp_f32_e32 v241, v241
	v_pk_mul_f32 v[234:235], v[84:85], v[234:235]
	v_pk_mul_f32 v[236:237], v[86:87], v[236:237]
	v_pk_mul_f32 v[238:239], v[80:81], v[238:239]
	v_pk_mul_f32 v[240:241], v[82:83], v[240:241]
	v_cvt_pk_bf16_f32 v84, v234, v235
	v_cvt_pk_bf16_f32 v85, v236, v237
	v_cvt_pk_bf16_f32 v86, v238, v239
	v_cvt_pk_bf16_f32 v87, v240, v241
	ds_write_b128 v228, v[84:87]
	ds_read_b128 v[80:83], v229
	v_pk_mul_f32 v[234:235], v[76:77], v[230:231]
	v_pk_mul_f32 v[236:237], v[78:79], v[230:231]
	v_pk_mul_f32 v[238:239], v[72:73], v[230:231]
	v_pk_mul_f32 v[240:241], v[74:75], v[230:231]
	v_exp_f32_e32 v234, v234
	v_exp_f32_e32 v235, v235
	v_exp_f32_e32 v236, v236
	v_exp_f32_e32 v237, v237
	v_exp_f32_e32 v238, v238
	v_exp_f32_e32 v239, v239
	v_exp_f32_e32 v240, v240
	v_exp_f32_e32 v241, v241
	v_pk_add_f32 v[234:235], v[234:235], v[232:233]
	v_pk_add_f32 v[236:237], v[236:237], v[232:233]
	v_pk_add_f32 v[238:239], v[238:239], v[232:233]
	v_pk_add_f32 v[240:241], v[240:241], v[232:233]
	v_rcp_f32_e32 v234, v234
	v_rcp_f32_e32 v235, v235
	v_rcp_f32_e32 v236, v236
	v_rcp_f32_e32 v237, v237
	v_rcp_f32_e32 v238, v238
	v_rcp_f32_e32 v239, v239
	v_rcp_f32_e32 v240, v240
	v_rcp_f32_e32 v241, v241
	v_pk_mul_f32 v[234:235], v[76:77], v[234:235]
	v_pk_mul_f32 v[236:237], v[78:79], v[236:237]
	v_pk_mul_f32 v[238:239], v[72:73], v[238:239]
	v_pk_mul_f32 v[240:241], v[74:75], v[240:241]
	v_cvt_pk_bf16_f32 v76, v234, v235
	v_cvt_pk_bf16_f32 v77, v236, v237
	v_cvt_pk_bf16_f32 v78, v238, v239
	v_cvt_pk_bf16_f32 v79, v240, v241
	ds_write_b128 v228, v[76:79]
	ds_read_b128 v[72:75], v229
	v_pk_mul_f32 v[234:235], v[68:69], v[230:231]
	v_pk_mul_f32 v[236:237], v[70:71], v[230:231]
	v_pk_mul_f32 v[238:239], v[64:65], v[230:231]
	v_pk_mul_f32 v[240:241], v[66:67], v[230:231]
	v_exp_f32_e32 v234, v234
	v_exp_f32_e32 v235, v235
	v_exp_f32_e32 v236, v236
	v_exp_f32_e32 v237, v237
	v_exp_f32_e32 v238, v238
	v_exp_f32_e32 v239, v239
	v_exp_f32_e32 v240, v240
	v_exp_f32_e32 v241, v241
	v_pk_add_f32 v[234:235], v[234:235], v[232:233]
	v_pk_add_f32 v[236:237], v[236:237], v[232:233]
	v_pk_add_f32 v[238:239], v[238:239], v[232:233]
	v_pk_add_f32 v[240:241], v[240:241], v[232:233]
	v_rcp_f32_e32 v234, v234
	v_rcp_f32_e32 v235, v235
	v_rcp_f32_e32 v236, v236
	v_rcp_f32_e32 v237, v237
	v_rcp_f32_e32 v238, v238
	v_rcp_f32_e32 v239, v239
	v_rcp_f32_e32 v240, v240
	v_rcp_f32_e32 v241, v241
	v_pk_mul_f32 v[234:235], v[68:69], v[234:235]
	v_pk_mul_f32 v[236:237], v[70:71], v[236:237]
	v_pk_mul_f32 v[238:239], v[64:65], v[238:239]
	v_pk_mul_f32 v[240:241], v[66:67], v[240:241]
	v_cvt_pk_bf16_f32 v68, v234, v235
	v_cvt_pk_bf16_f32 v69, v236, v237
	v_cvt_pk_bf16_f32 v70, v238, v239
	v_cvt_pk_bf16_f32 v71, v240, v241
	ds_write_b128 v228, v[68:71]
	ds_read_b128 v[64:67], v229
	v_pk_mov_b32 v[92:93], 0, 0
	v_pk_mov_b32 v[94:95], 0, 0
	v_pk_mov_b32 v[84:85], 0, 0
	v_pk_mov_b32 v[86:87], 0, 0
	v_pk_mov_b32 v[76:77], 0, 0
	v_pk_mov_b32 v[78:79], 0, 0
	v_pk_mov_b32 v[68:69], 0, 0
	v_pk_mov_b32 v[70:71], 0, 0
	v_add_u32_e32 v160, s100, v160
	s_waitcnt lgkmcnt(6)
	global_store_dwordx4 v160, v[88:91], s[98:99] nt
	s_waitcnt lgkmcnt(4)
	global_store_dwordx4 v160, v[80:83], s[98:99] offset:256 nt
	v_add_u32_e32 v160, s100, v160
	s_waitcnt lgkmcnt(2)
	global_store_dwordx4 v160, v[72:75], s[98:99] nt
	s_waitcnt lgkmcnt(0)
; __device__ __forceinline__ u32x4 pack8(const float (&f)[8]) { u32x4 w; w.x = cvt_pk_bf16(f[0], f[1]); w.y = cvt_pk_bf16(f[2], f[3]); w.z = cvt_pk_bf16(f[4], f[5]); w.w = cvt_pk_bf16(f[6], f[7]); return w; }
; __device__ __forceinline__ float sigm(float x) { return __builtin_amdgcn_rcpf(1.f + __builtin_amdgcn_exp2f(-1.4426950408889634f * x)); }
;     __device__ __forceinline__ void operator()(const f32x4 (&acc)[2][2][4][2], const Unit& u, int wr, int wc, int fr, int fq) const {
;     ...
;                     } else if (act == 2) {
; #pragma unroll
;                         for (int e = 0; e < 8; ++e) f[e] = f[e] * sigm(f[e]);
;                     }
;                     __builtin_nontemporal_store(pack8(f), (u32x4*)(rowp + bj * HALF)); } }
; template <class Epi, class Sched, bool ALIGN_EPI = false, bool SP2 = false>
; __device__ __forceinline__ void gemm_phase(PG8_LAS unsigned char* lds, const Gemm g, const Sched& S, const Epi& E) {
;     ...
; #pragma unroll
;         for (int a = 0; a < 2; ++a)
; #pragma unroll
;             for (int b = 0; b < 2; ++b)
; #pragma unroll
;                 for (int m = 0; m < 4; ++m)
; #pragma unroll
;                     for (int n = 0; n < 2; ++n) acc[a][b][m][n] = (f32x4){0.f, 0.f, 0.f, 0.f};
;         cur = nxt; cA = nA; cB = nB; ++ui;
	global_store_dwordx4 v160, v[64:67], s[98:99] offset:256 nt
	v_pk_mov_b32 v[88:89], 0, 0
	v_pk_mov_b32 v[90:91], 0, 0
	v_pk_mov_b32 v[80:81], 0, 0
	v_pk_mov_b32 v[82:83], 0, 0
	v_pk_mov_b32 v[72:73], 0, 0
	v_pk_mov_b32 v[74:75], 0, 0
	v_pk_mov_b32 v[64:65], 0, 0
	v_pk_mov_b32 v[66:67], 0, 0
	v_pk_mul_f32 v[234:235], v[60:61], v[230:231]
	v_pk_mul_f32 v[236:237], v[62:63], v[230:231]
	v_pk_mul_f32 v[238:239], v[56:57], v[230:231]
	v_pk_mul_f32 v[240:241], v[58:59], v[230:231]
	v_exp_f32_e32 v234, v234
	v_exp_f32_e32 v235, v235
	v_exp_f32_e32 v236, v236
	v_exp_f32_e32 v237, v237
	v_exp_f32_e32 v238, v238
	v_exp_f32_e32 v239, v239
	v_exp_f32_e32 v240, v240
	v_exp_f32_e32 v241, v241
	v_pk_add_f32 v[234:235], v[234:235], v[232:233]
	v_pk_add_f32 v[236:237], v[236:237], v[232:233]
	v_pk_add_f32 v[238:239], v[238:239], v[232:233]
	v_pk_add_f32 v[240:241], v[240:241], v[232:233]
	v_rcp_f32_e32 v234, v234
	v_rcp_f32_e32 v235, v235
	v_rcp_f32_e32 v236, v236
	v_rcp_f32_e32 v237, v237
	v_rcp_f32_e32 v238, v238
	v_rcp_f32_e32 v239, v239
	v_rcp_f32_e32 v240, v240
	v_rcp_f32_e32 v241, v241
	v_pk_mul_f32 v[234:235], v[60:61], v[234:235]
	v_pk_mul_f32 v[236:237], v[62:63], v[236:237]
	v_pk_mul_f32 v[238:239], v[56:57], v[238:239]
	v_pk_mul_f32 v[240:241], v[58:59], v[240:241]
	v_cvt_pk_bf16_f32 v60, v234, v235
	v_cvt_pk_bf16_f32 v61, v236, v237
	v_cvt_pk_bf16_f32 v62, v238, v239
	v_cvt_pk_bf16_f32 v63, v240, v241
	ds_write_b128 v228, v[60:63]
	ds_read_b128 v[56:59], v229
	v_pk_mul_f32 v[234:235], v[52:53], v[230:231]
	v_pk_mul_f32 v[236:237], v[54:55], v[230:231]
	v_pk_mul_f32 v[238:239], v[48:49], v[230:231]
	v_pk_mul_f32 v[240:241], v[50:51], v[230:231]
	v_exp_f32_e32 v234, v234
	v_exp_f32_e32 v235, v235
	v_exp_f32_e32 v236, v236
	v_exp_f32_e32 v237, v237
	v_exp_f32_e32 v238, v238
	v_exp_f32_e32 v239, v239
	v_exp_f32_e32 v240, v240
	v_exp_f32_e32 v241, v241
	v_pk_add_f32 v[234:235], v[234:235], v[232:233]
	v_pk_add_f32 v[236:237], v[236:237], v[232:233]
	v_pk_add_f32 v[238:239], v[238:239], v[232:233]
	v_pk_add_f32 v[240:241], v[240:241], v[232:233]
	v_rcp_f32_e32 v234, v234
	v_rcp_f32_e32 v235, v235
	v_rcp_f32_e32 v236, v236
	v_rcp_f32_e32 v237, v237
	v_rcp_f32_e32 v238, v238
	v_rcp_f32_e32 v239, v239
	v_rcp_f32_e32 v240, v240
	v_rcp_f32_e32 v241, v241
	v_pk_mul_f32 v[234:235], v[52:53], v[234:235]
	v_pk_mul_f32 v[236:237], v[54:55], v[236:237]
	v_pk_mul_f32 v[238:239], v[48:49], v[238:239]
	v_pk_mul_f32 v[240:241], v[50:51], v[240:241]
	v_cvt_pk_bf16_f32 v52, v234, v235
	v_cvt_pk_bf16_f32 v53, v236, v237
	v_cvt_pk_bf16_f32 v54, v238, v239
	v_cvt_pk_bf16_f32 v55, v240, v241
	ds_write_b128 v228, v[52:55]
	ds_read_b128 v[48:51], v229
	v_pk_mul_f32 v[234:235], v[44:45], v[230:231]
	v_pk_mul_f32 v[236:237], v[46:47], v[230:231]
	v_pk_mul_f32 v[238:239], v[40:41], v[230:231]
	v_pk_mul_f32 v[240:241], v[42:43], v[230:231]
	v_exp_f32_e32 v234, v234
	v_exp_f32_e32 v235, v235
	v_exp_f32_e32 v236, v236
	v_exp_f32_e32 v237, v237
	v_exp_f32_e32 v238, v238
	v_exp_f32_e32 v239, v239
	v_exp_f32_e32 v240, v240
	v_exp_f32_e32 v241, v241
	v_pk_add_f32 v[234:235], v[234:235], v[232:233]
	v_pk_add_f32 v[236:237], v[236:237], v[232:233]
	v_pk_add_f32 v[238:239], v[238:239], v[232:233]
	v_pk_add_f32 v[240:241], v[240:241], v[232:233]
	v_rcp_f32_e32 v234, v234
	v_rcp_f32_e32 v235, v235
	v_rcp_f32_e32 v236, v236
	v_rcp_f32_e32 v237, v237
	v_rcp_f32_e32 v238, v238
	v_rcp_f32_e32 v239, v239
	v_rcp_f32_e32 v240, v240
	v_rcp_f32_e32 v241, v241
	v_pk_mul_f32 v[234:235], v[44:45], v[234:235]
	v_pk_mul_f32 v[236:237], v[46:47], v[236:237]
	v_pk_mul_f32 v[238:239], v[40:41], v[238:239]
	v_pk_mul_f32 v[240:241], v[42:43], v[240:241]
	v_cvt_pk_bf16_f32 v44, v234, v235
	v_cvt_pk_bf16_f32 v45, v236, v237
	v_cvt_pk_bf16_f32 v46, v238, v239
	v_cvt_pk_bf16_f32 v47, v240, v241
	ds_write_b128 v228, v[44:47]
	ds_read_b128 v[40:43], v229
	v_pk_mul_f32 v[234:235], v[36:37], v[230:231]
	v_pk_mul_f32 v[236:237], v[38:39], v[230:231]
	v_pk_mul_f32 v[238:239], v[32:33], v[230:231]
	v_pk_mul_f32 v[240:241], v[34:35], v[230:231]
	v_exp_f32_e32 v234, v234
	v_exp_f32_e32 v235, v235
	v_exp_f32_e32 v236, v236
	v_exp_f32_e32 v237, v237
	v_exp_f32_e32 v238, v238
	v_exp_f32_e32 v239, v239
	v_exp_f32_e32 v240, v240
	v_exp_f32_e32 v241, v241
	v_pk_add_f32 v[234:235], v[234:235], v[232:233]
	v_pk_add_f32 v[236:237], v[236:237], v[232:233]
	v_pk_add_f32 v[238:239], v[238:239], v[232:233]
	v_pk_add_f32 v[240:241], v[240:241], v[232:233]
	v_rcp_f32_e32 v234, v234
	v_rcp_f32_e32 v235, v235
	v_rcp_f32_e32 v236, v236
	v_rcp_f32_e32 v237, v237
	v_rcp_f32_e32 v238, v238
	v_rcp_f32_e32 v239, v239
	v_rcp_f32_e32 v240, v240
	v_rcp_f32_e32 v241, v241
	v_pk_mul_f32 v[234:235], v[36:37], v[234:235]
	v_pk_mul_f32 v[236:237], v[38:39], v[236:237]
	v_pk_mul_f32 v[238:239], v[32:33], v[238:239]
	v_pk_mul_f32 v[240:241], v[34:35], v[240:241]
	v_cvt_pk_bf16_f32 v36, v234, v235
	v_cvt_pk_bf16_f32 v37, v236, v237
	v_cvt_pk_bf16_f32 v38, v238, v239
	v_cvt_pk_bf16_f32 v39, v240, v241
	ds_write_b128 v228, v[36:39]
	ds_read_b128 v[32:35], v229
	v_pk_mov_b32 v[60:61], 0, 0
	v_pk_mov_b32 v[62:63], 0, 0
	v_pk_mov_b32 v[52:53], 0, 0
	v_pk_mov_b32 v[54:55], 0, 0
	v_pk_mov_b32 v[44:45], 0, 0
	v_pk_mov_b32 v[46:47], 0, 0
	v_pk_mov_b32 v[36:37], 0, 0
	v_pk_mov_b32 v[38:39], 0, 0
	v_mad_u32_u24 v160, s100, 5, v160
	s_waitcnt lgkmcnt(6)
	global_store_dwordx4 v160, v[56:59], s[98:99] nt
	s_waitcnt lgkmcnt(4)
	global_store_dwordx4 v160, v[48:51], s[98:99] offset:256 nt
	v_add_u32_e32 v160, s100, v160
	s_waitcnt lgkmcnt(2)
	global_store_dwordx4 v160, v[40:43], s[98:99] nt
	s_waitcnt lgkmcnt(0)
; __device__ __forceinline__ u32x4 pack8(const float (&f)[8]) { u32x4 w; w.x = cvt_pk_bf16(f[0], f[1]); w.y = cvt_pk_bf16(f[2], f[3]); w.z = cvt_pk_bf16(f[4], f[5]); w.w = cvt_pk_bf16(f[6], f[7]); return w; }
; __device__ __forceinline__ float sigm(float x) { return __builtin_amdgcn_rcpf(1.f + __builtin_amdgcn_exp2f(-1.4426950408889634f * x)); }
;     __device__ __forceinline__ void operator()(const f32x4 (&acc)[2][2][4][2], const Unit& u, int wr, int wc, int fr, int fq) const {
;     ...
;             for (int m = 0; m < 4; ++m) { bf16_t* rowp = base + (size_t)(row0 + ai * HALF + m * 16) * ldc + col0;
; #pragma unroll
;                 for (int bj = 0; bj < 2; ++bj) { const f32x4 v0 = acc[ai][bj][m][0], v1 = acc[ai][bj][m][1];
;                     float f[8] = {v0[0], v0[1], v0[2], v0[3], v1[0], v1[1], v1[2], v1[3]};
;                     if (act == 1) {
; #pragma unroll
;                         for (int e = 0; e < 8; ++e) f[e] = sigm(f[e]);
;                     } else if (act == 2) {
; #pragma unroll
;                         for (int e = 0; e < 8; ++e) f[e] = f[e] * sigm(f[e]);
;                     }
;                     __builtin_nontemporal_store(pack8(f), (u32x4*)(rowp + bj * HALF)); } }
	global_store_dwordx4 v160, v[32:35], s[98:99] offset:256 nt
	v_pk_mov_b32 v[56:57], 0, 0
	v_pk_mov_b32 v[58:59], 0, 0
	v_pk_mov_b32 v[48:49], 0, 0
	v_pk_mov_b32 v[50:51], 0, 0
	v_pk_mov_b32 v[40:41], 0, 0
	v_pk_mov_b32 v[42:43], 0, 0
	v_pk_mov_b32 v[32:33], 0, 0
	v_pk_mov_b32 v[34:35], 0, 0
	v_pk_mul_f32 v[234:235], v[28:29], v[230:231]
	v_pk_mul_f32 v[236:237], v[30:31], v[230:231]
	v_pk_mul_f32 v[238:239], v[24:25], v[230:231]
	v_pk_mul_f32 v[240:241], v[26:27], v[230:231]
	v_exp_f32_e32 v234, v234
	v_exp_f32_e32 v235, v235
	v_exp_f32_e32 v236, v236
	v_exp_f32_e32 v237, v237
	v_exp_f32_e32 v238, v238
	v_exp_f32_e32 v239, v239
	v_exp_f32_e32 v240, v240
	v_exp_f32_e32 v241, v241
	v_pk_add_f32 v[234:235], v[234:235], v[232:233]
	v_pk_add_f32 v[236:237], v[236:237], v[232:233]
	v_pk_add_f32 v[238:239], v[238:239], v[232:233]
	v_pk_add_f32 v[240:241], v[240:241], v[232:233]
	v_rcp_f32_e32 v234, v234
	v_rcp_f32_e32 v235, v235
	v_rcp_f32_e32 v236, v236
	v_rcp_f32_e32 v237, v237
	v_rcp_f32_e32 v238, v238
	v_rcp_f32_e32 v239, v239
	v_rcp_f32_e32 v240, v240
	v_rcp_f32_e32 v241, v241
	v_pk_mul_f32 v[234:235], v[28:29], v[234:235]
	v_pk_mul_f32 v[236:237], v[30:31], v[236:237]
	v_pk_mul_f32 v[238:239], v[24:25], v[238:239]
	v_pk_mul_f32 v[240:241], v[26:27], v[240:241]
	v_cvt_pk_bf16_f32 v28, v234, v235
	v_cvt_pk_bf16_f32 v29, v236, v237
	v_cvt_pk_bf16_f32 v30, v238, v239
	v_cvt_pk_bf16_f32 v31, v240, v241
	ds_write_b128 v228, v[28:31]
	ds_read_b128 v[24:27], v229
	v_pk_mul_f32 v[234:235], v[20:21], v[230:231]
	v_pk_mul_f32 v[236:237], v[22:23], v[230:231]
	v_pk_mul_f32 v[238:239], v[16:17], v[230:231]
	v_pk_mul_f32 v[240:241], v[18:19], v[230:231]
	v_exp_f32_e32 v234, v234
	v_exp_f32_e32 v235, v235
	v_exp_f32_e32 v236, v236
	v_exp_f32_e32 v237, v237
	v_exp_f32_e32 v238, v238
	v_exp_f32_e32 v239, v239
	v_exp_f32_e32 v240, v240
	v_exp_f32_e32 v241, v241
	v_pk_add_f32 v[234:235], v[234:235], v[232:233]
	v_pk_add_f32 v[236:237], v[236:237], v[232:233]
	v_pk_add_f32 v[238:239], v[238:239], v[232:233]
	v_pk_add_f32 v[240:241], v[240:241], v[232:233]
	v_rcp_f32_e32 v234, v234
	v_rcp_f32_e32 v235, v235
	v_rcp_f32_e32 v236, v236
	v_rcp_f32_e32 v237, v237
	v_rcp_f32_e32 v238, v238
	v_rcp_f32_e32 v239, v239
	v_rcp_f32_e32 v240, v240
	v_rcp_f32_e32 v241, v241
	v_pk_mul_f32 v[234:235], v[20:21], v[234:235]
	v_pk_mul_f32 v[236:237], v[22:23], v[236:237]
	v_pk_mul_f32 v[238:239], v[16:17], v[238:239]
	v_pk_mul_f32 v[240:241], v[18:19], v[240:241]
	v_cvt_pk_bf16_f32 v20, v234, v235
	v_cvt_pk_bf16_f32 v21, v236, v237
	v_cvt_pk_bf16_f32 v22, v238, v239
	v_cvt_pk_bf16_f32 v23, v240, v241
	ds_write_b128 v228, v[20:23]
	ds_read_b128 v[16:19], v229
	v_pk_mul_f32 v[234:235], v[12:13], v[230:231]
	v_pk_mul_f32 v[236:237], v[14:15], v[230:231]
	v_pk_mul_f32 v[238:239], v[8:9], v[230:231]
	v_pk_mul_f32 v[240:241], v[10:11], v[230:231]
	v_exp_f32_e32 v234, v234
	v_exp_f32_e32 v235, v235
	v_exp_f32_e32 v236, v236
	v_exp_f32_e32 v237, v237
	v_exp_f32_e32 v238, v238
	v_exp_f32_e32 v239, v239
	v_exp_f32_e32 v240, v240
	v_exp_f32_e32 v241, v241
	v_pk_add_f32 v[234:235], v[234:235], v[232:233]
	v_pk_add_f32 v[236:237], v[236:237], v[232:233]
	v_pk_add_f32 v[238:239], v[238:239], v[232:233]
	v_pk_add_f32 v[240:241], v[240:241], v[232:233]
	v_rcp_f32_e32 v234, v234
	v_rcp_f32_e32 v235, v235
	v_rcp_f32_e32 v236, v236
	v_rcp_f32_e32 v237, v237
	v_rcp_f32_e32 v238, v238
	v_rcp_f32_e32 v239, v239
	v_rcp_f32_e32 v240, v240
	v_rcp_f32_e32 v241, v241
	v_pk_mul_f32 v[234:235], v[12:13], v[234:235]
	v_pk_mul_f32 v[236:237], v[14:15], v[236:237]
	v_pk_mul_f32 v[238:239], v[8:9], v[238:239]
	v_pk_mul_f32 v[240:241], v[10:11], v[240:241]
	v_cvt_pk_bf16_f32 v12, v234, v235
	v_cvt_pk_bf16_f32 v13, v236, v237
	v_cvt_pk_bf16_f32 v14, v238, v239
	v_cvt_pk_bf16_f32 v15, v240, v241
	ds_write_b128 v228, v[12:15]
	ds_read_b128 v[8:11], v229
	v_pk_mul_f32 v[234:235], v[4:5], v[230:231]
	v_pk_mul_f32 v[236:237], v[6:7], v[230:231]
	v_pk_mul_f32 v[238:239], v[0:1], v[230:231]
	v_pk_mul_f32 v[240:241], v[2:3], v[230:231]
	v_exp_f32_e32 v234, v234
	v_exp_f32_e32 v235, v235
	v_exp_f32_e32 v236, v236
	v_exp_f32_e32 v237, v237
	v_exp_f32_e32 v238, v238
	v_exp_f32_e32 v239, v239
	v_exp_f32_e32 v240, v240
	v_exp_f32_e32 v241, v241
	v_pk_add_f32 v[234:235], v[234:235], v[232:233]
	v_pk_add_f32 v[236:237], v[236:237], v[232:233]
	v_pk_add_f32 v[238:239], v[238:239], v[232:233]
	v_pk_add_f32 v[240:241], v[240:241], v[232:233]
	v_rcp_f32_e32 v234, v234
	v_rcp_f32_e32 v235, v235
	v_rcp_f32_e32 v236, v236
	v_rcp_f32_e32 v237, v237
	v_rcp_f32_e32 v238, v238
	v_rcp_f32_e32 v239, v239
	v_rcp_f32_e32 v240, v240
	v_rcp_f32_e32 v241, v241
	v_pk_mul_f32 v[234:235], v[4:5], v[234:235]
	v_pk_mul_f32 v[236:237], v[6:7], v[236:237]
	v_pk_mul_f32 v[238:239], v[0:1], v[238:239]
	v_pk_mul_f32 v[240:241], v[2:3], v[240:241]
	v_cvt_pk_bf16_f32 v4, v234, v235
	v_cvt_pk_bf16_f32 v5, v236, v237
	v_cvt_pk_bf16_f32 v6, v238, v239
	v_cvt_pk_bf16_f32 v7, v240, v241
	ds_write_b128 v228, v[4:7]
	ds_read_b128 v[0:3], v229
	v_pk_mov_b32 v[28:29], 0, 0
	v_pk_mov_b32 v[30:31], 0, 0
	v_pk_mov_b32 v[20:21], 0, 0
	v_pk_mov_b32 v[22:23], 0, 0
	v_pk_mov_b32 v[12:13], 0, 0
	v_pk_mov_b32 v[14:15], 0, 0
	v_pk_mov_b32 v[4:5], 0, 0
	v_pk_mov_b32 v[6:7], 0, 0
	v_add_u32_e32 v160, s100, v160
	s_waitcnt lgkmcnt(6)
	global_store_dwordx4 v160, v[24:27], s[98:99] nt
	s_waitcnt lgkmcnt(4)
	global_store_dwordx4 v160, v[16:19], s[98:99] offset:256 nt
	v_add_u32_e32 v160, s100, v160
	s_waitcnt lgkmcnt(2)
	global_store_dwordx4 v160, v[8:11], s[98:99] nt
	s_waitcnt lgkmcnt(0)
	global_store_dwordx4 v160, v[0:3], s[98:99] offset:256 nt
	v_pk_mov_b32 v[24:25], 0, 0
	v_pk_mov_b32 v[26:27], 0, 0
	v_pk_mov_b32 v[16:17], 0, 0
	v_pk_mov_b32 v[18:19], 0, 0
	v_pk_mov_b32 v[8:9], 0, 0
	v_pk_mov_b32 v[10:11], 0, 0
	v_pk_mov_b32 v[0:1], 0, 0
	v_pk_mov_b32 v[2:3], 0, 0
	s_andn2_b64 vcc, exec, s[0:1]
	s_mov_b64 s[0:1], -1
	s_branch .Lp1_tail
; __device__ __forceinline__ u32x4 pack8(const float (&f)[8]) { u32x4 w; w.x = cvt_pk_bf16(f[0], f[1]); w.y = cvt_pk_bf16(f[2], f[3]); w.z = cvt_pk_bf16(f[4], f[5]); w.w = cvt_pk_bf16(f[6], f[7]); return w; }
; __device__ __forceinline__ float sigm(float x) { return __builtin_amdgcn_rcpf(1.f + __builtin_amdgcn_exp2f(-1.4426950408889634f * x)); }
;     __device__ __forceinline__ void operator()(const f32x4 (&acc)[2][2][4][2], const Unit& u, int wr, int wc, int fr, int fq) const {
;     ...
;             for (int m = 0; m < 4; ++m) { bf16_t* rowp = base + (size_t)(row0 + ai * HALF + m * 16) * ldc + col0;
; #pragma unroll
;                 for (int bj = 0; bj < 2; ++bj) { const f32x4 v0 = acc[ai][bj][m][0], v1 = acc[ai][bj][m][1];
;                     float f[8] = {v0[0], v0[1], v0[2], v0[3], v1[0], v1[1], v1[2], v1[3]};
;                     if (act == 1) {
; #pragma unroll
;                         for (int e = 0; e < 8; ++e) f[e] = sigm(f[e]);
;                     } else if (act == 2) {
; #pragma unroll
;                         for (int e = 0; e < 8; ++e) f[e] = f[e] * sigm(f[e]);
;                     }
;                     __builtin_nontemporal_store(pack8(f), (u32x4*)(rowp + bj * HALF)); } }
.Lp1_sig:
	v_lshl_add_u32 v160, s6, 8, v154
	v_add_u32_e32 v136, s3, v156
	s_add_u32 s98, s68, s80
	s_addc_u32 s99, s69, s81
	s_lshl_b32 s100, s78, 1
	v_mul_lo_u32 v160, v160, s100
	s_lshl_b32 s100, s78, 5
	v_lshl_add_u32 v160, v136, 1, v160
	v_mov_b32_e32 v230, 0xbfb8aa3b
	v_mov_b32_e32 v231, 0xbfb8aa3b
	v_mov_b32_e32 v232, 1.0
	v_mov_b32_e32 v233, 1.0
	v_pk_mul_f32 v[234:235], v[124:125], v[230:231]
	v_pk_mul_f32 v[236:237], v[126:127], v[230:231]
	v_pk_mul_f32 v[238:239], v[120:121], v[230:231]
	v_pk_mul_f32 v[240:241], v[122:123], v[230:231]
	v_exp_f32_e32 v234, v234
	v_exp_f32_e32 v235, v235
	v_exp_f32_e32 v236, v236
	v_exp_f32_e32 v237, v237
	v_exp_f32_e32 v238, v238
	v_exp_f32_e32 v239, v239
	v_exp_f32_e32 v240, v240
	v_exp_f32_e32 v241, v241
	v_pk_add_f32 v[234:235], v[234:235], v[232:233]
	v_pk_add_f32 v[236:237], v[236:237], v[232:233]
	v_pk_add_f32 v[238:239], v[238:239], v[232:233]
	v_pk_add_f32 v[240:241], v[240:241], v[232:233]
	v_rcp_f32_e32 v234, v234
	v_rcp_f32_e32 v235, v235
	v_rcp_f32_e32 v236, v236
	v_rcp_f32_e32 v237, v237
	v_rcp_f32_e32 v238, v238
	v_rcp_f32_e32 v239, v239
	v_rcp_f32_e32 v240, v240
	v_rcp_f32_e32 v241, v241
	s_nop 0
	v_cvt_pk_bf16_f32 v124, v234, v235
	v_cvt_pk_bf16_f32 v125, v236, v237
	v_cvt_pk_bf16_f32 v126, v238, v239
	v_cvt_pk_bf16_f32 v127, v240, v241
	ds_write_b128 v228, v[124:127]
	ds_read_b128 v[120:123], v229
	v_pk_mul_f32 v[234:235], v[116:117], v[230:231]
	v_pk_mul_f32 v[236:237], v[118:119], v[230:231]
	v_pk_mul_f32 v[238:239], v[112:113], v[230:231]
	v_pk_mul_f32 v[240:241], v[114:115], v[230:231]
	v_exp_f32_e32 v234, v234
	v_exp_f32_e32 v235, v235
	v_exp_f32_e32 v236, v236
	v_exp_f32_e32 v237, v237
	v_exp_f32_e32 v238, v238
	v_exp_f32_e32 v239, v239
	v_exp_f32_e32 v240, v240
	v_exp_f32_e32 v241, v241
	v_pk_add_f32 v[234:235], v[234:235], v[232:233]
	v_pk_add_f32 v[236:237], v[236:237], v[232:233]
	v_pk_add_f32 v[238:239], v[238:239], v[232:233]
	v_pk_add_f32 v[240:241], v[240:241], v[232:233]
	v_rcp_f32_e32 v234, v234
	v_rcp_f32_e32 v235, v235
	v_rcp_f32_e32 v236, v236
	v_rcp_f32_e32 v237, v237
	v_rcp_f32_e32 v238, v238
	v_rcp_f32_e32 v239, v239
	v_rcp_f32_e32 v240, v240
	v_rcp_f32_e32 v241, v241
	s_nop 0
	v_cvt_pk_bf16_f32 v116, v234, v235
	v_cvt_pk_bf16_f32 v117, v236, v237
	v_cvt_pk_bf16_f32 v118, v238, v239
	v_cvt_pk_bf16_f32 v119, v240, v241
	ds_write_b128 v228, v[116:119]
	ds_read_b128 v[112:115], v229
	v_pk_mul_f32 v[234:235], v[108:109], v[230:231]
	v_pk_mul_f32 v[236:237], v[110:111], v[230:231]
	v_pk_mul_f32 v[238:239], v[104:105], v[230:231]
	v_pk_mul_f32 v[240:241], v[106:107], v[230:231]
	v_exp_f32_e32 v234, v234
	v_exp_f32_e32 v235, v235
	v_exp_f32_e32 v236, v236
	v_exp_f32_e32 v237, v237
	v_exp_f32_e32 v238, v238
	v_exp_f32_e32 v239, v239
	v_exp_f32_e32 v240, v240
	v_exp_f32_e32 v241, v241
	v_pk_add_f32 v[234:235], v[234:235], v[232:233]
	v_pk_add_f32 v[236:237], v[236:237], v[232:233]
	v_pk_add_f32 v[238:239], v[238:239], v[232:233]
	v_pk_add_f32 v[240:241], v[240:241], v[232:233]
	v_rcp_f32_e32 v234, v234
	v_rcp_f32_e32 v235, v235
	v_rcp_f32_e32 v236, v236
	v_rcp_f32_e32 v237, v237
	v_rcp_f32_e32 v238, v238
	v_rcp_f32_e32 v239, v239
	v_rcp_f32_e32 v240, v240
	v_rcp_f32_e32 v241, v241
	s_nop 0
	v_cvt_pk_bf16_f32 v108, v234, v235
	v_cvt_pk_bf16_f32 v109, v236, v237
	v_cvt_pk_bf16_f32 v110, v238, v239
	v_cvt_pk_bf16_f32 v111, v240, v241
	ds_write_b128 v228, v[108:111]
	ds_read_b128 v[104:107], v229
	v_pk_mul_f32 v[234:235], v[100:101], v[230:231]
	v_pk_mul_f32 v[236:237], v[102:103], v[230:231]
	v_pk_mul_f32 v[238:239], v[96:97], v[230:231]
	v_pk_mul_f32 v[240:241], v[98:99], v[230:231]
	v_exp_f32_e32 v234, v234
	v_exp_f32_e32 v235, v235
	v_exp_f32_e32 v236, v236
	v_exp_f32_e32 v237, v237
	v_exp_f32_e32 v238, v238
	v_exp_f32_e32 v239, v239
	v_exp_f32_e32 v240, v240
	v_exp_f32_e32 v241, v241
	v_pk_add_f32 v[234:235], v[234:235], v[232:233]
	v_pk_add_f32 v[236:237], v[236:237], v[232:233]
	v_pk_add_f32 v[238:239], v[238:239], v[232:233]
	v_pk_add_f32 v[240:241], v[240:241], v[232:233]
	v_rcp_f32_e32 v234, v234
	v_rcp_f32_e32 v235, v235
	v_rcp_f32_e32 v236, v236
	v_rcp_f32_e32 v237, v237
	v_rcp_f32_e32 v238, v238
	v_rcp_f32_e32 v239, v239
	v_rcp_f32_e32 v240, v240
	v_rcp_f32_e32 v241, v241
	s_nop 0
	v_cvt_pk_bf16_f32 v100, v234, v235
	v_cvt_pk_bf16_f32 v101, v236, v237
	v_cvt_pk_bf16_f32 v102, v238, v239
	v_cvt_pk_bf16_f32 v103, v240, v241
	ds_write_b128 v228, v[100:103]
	ds_read_b128 v[96:99], v229
	v_pk_mov_b32 v[124:125], 0, 0
	v_pk_mov_b32 v[126:127], 0, 0
	v_pk_mov_b32 v[116:117], 0, 0
	v_pk_mov_b32 v[118:119], 0, 0
	v_pk_mov_b32 v[108:109], 0, 0
	v_pk_mov_b32 v[110:111], 0, 0
	v_pk_mov_b32 v[100:101], 0, 0
	v_pk_mov_b32 v[102:103], 0, 0
	s_waitcnt lgkmcnt(6)
	global_store_dwordx4 v160, v[120:123], s[98:99] nt
	s_waitcnt lgkmcnt(4)
	global_store_dwordx4 v160, v[112:115], s[98:99] offset:256 nt
	v_add_u32_e32 v160, s100, v160
	s_waitcnt lgkmcnt(2)
	global_store_dwordx4 v160, v[104:107], s[98:99] nt
	s_waitcnt lgkmcnt(0)
; __device__ __forceinline__ u32x4 pack8(const float (&f)[8]) { u32x4 w; w.x = cvt_pk_bf16(f[0], f[1]); w.y = cvt_pk_bf16(f[2], f[3]); w.z = cvt_pk_bf16(f[4], f[5]); w.w = cvt_pk_bf16(f[6], f[7]); return w; }
; __device__ __forceinline__ float sigm(float x) { return __builtin_amdgcn_rcpf(1.f + __builtin_amdgcn_exp2f(-1.4426950408889634f * x)); }
;     __device__ __forceinline__ void operator()(const f32x4 (&acc)[2][2][4][2], const Unit& u, int wr, int wc, int fr, int fq) const {
;     ...
;             for (int m = 0; m < 4; ++m) { bf16_t* rowp = base + (size_t)(row0 + ai * HALF + m * 16) * ldc + col0;
; #pragma unroll
;                 for (int bj = 0; bj < 2; ++bj) { const f32x4 v0 = acc[ai][bj][m][0], v1 = acc[ai][bj][m][1];
;                     float f[8] = {v0[0], v0[1], v0[2], v0[3], v1[0], v1[1], v1[2], v1[3]};
;                     if (act == 1) {
; #pragma unroll
;                         for (int e = 0; e < 8; ++e) f[e] = sigm(f[e]);
;                     } else if (act == 2) {
; #pragma unroll
;                         for (int e = 0; e < 8; ++e) f[e] = f[e] * sigm(f[e]);
;                     }
;                     __builtin_nontemporal_store(pack8(f), (u32x4*)(rowp + bj * HALF)); } }
	global_store_dwordx4 v160, v[96:99], s[98:99] offset:256 nt
	v_pk_mov_b32 v[120:121], 0, 0
	v_pk_mov_b32 v[122:123], 0, 0
	v_pk_mov_b32 v[112:113], 0, 0
	v_pk_mov_b32 v[114:115], 0, 0
	v_pk_mov_b32 v[104:105], 0, 0
	v_pk_mov_b32 v[106:107], 0, 0
	v_pk_mov_b32 v[96:97], 0, 0
	v_pk_mov_b32 v[98:99], 0, 0
	v_pk_mul_f32 v[234:235], v[92:93], v[230:231]
	v_pk_mul_f32 v[236:237], v[94:95], v[230:231]
	v_pk_mul_f32 v[238:239], v[88:89], v[230:231]
	v_pk_mul_f32 v[240:241], v[90:91], v[230:231]
	v_exp_f32_e32 v234, v234
	v_exp_f32_e32 v235, v235
	v_exp_f32_e32 v236, v236
	v_exp_f32_e32 v237, v237
	v_exp_f32_e32 v238, v238
	v_exp_f32_e32 v239, v239
	v_exp_f32_e32 v240, v240
	v_exp_f32_e32 v241, v241
	v_pk_add_f32 v[234:235], v[234:235], v[232:233]
	v_pk_add_f32 v[236:237], v[236:237], v[232:233]
	v_pk_add_f32 v[238:239], v[238:239], v[232:233]
	v_pk_add_f32 v[240:241], v[240:241], v[232:233]
	v_rcp_f32_e32 v234, v234
	v_rcp_f32_e32 v235, v235
	v_rcp_f32_e32 v236, v236
	v_rcp_f32_e32 v237, v237
	v_rcp_f32_e32 v238, v238
	v_rcp_f32_e32 v239, v239
	v_rcp_f32_e32 v240, v240
	v_rcp_f32_e32 v241, v241
	s_nop 0
	v_cvt_pk_bf16_f32 v92, v234, v235
	v_cvt_pk_bf16_f32 v93, v236, v237
	v_cvt_pk_bf16_f32 v94, v238, v239
	v_cvt_pk_bf16_f32 v95, v240, v241
	ds_write_b128 v228, v[92:95]
	ds_read_b128 v[88:91], v229
	v_pk_mul_f32 v[234:235], v[84:85], v[230:231]
	v_pk_mul_f32 v[236:237], v[86:87], v[230:231]
	v_pk_mul_f32 v[238:239], v[80:81], v[230:231]
	v_pk_mul_f32 v[240:241], v[82:83], v[230:231]
	v_exp_f32_e32 v234, v234
	v_exp_f32_e32 v235, v235
	v_exp_f32_e32 v236, v236
	v_exp_f32_e32 v237, v237
	v_exp_f32_e32 v238, v238
	v_exp_f32_e32 v239, v239
	v_exp_f32_e32 v240, v240
	v_exp_f32_e32 v241, v241
	v_pk_add_f32 v[234:235], v[234:235], v[232:233]
	v_pk_add_f32 v[236:237], v[236:237], v[232:233]
	v_pk_add_f32 v[238:239], v[238:239], v[232:233]
	v_pk_add_f32 v[240:241], v[240:241], v[232:233]
	v_rcp_f32_e32 v234, v234
	v_rcp_f32_e32 v235, v235
	v_rcp_f32_e32 v236, v236
	v_rcp_f32_e32 v237, v237
	v_rcp_f32_e32 v238, v238
	v_rcp_f32_e32 v239, v239
	v_rcp_f32_e32 v240, v240
	v_rcp_f32_e32 v241, v241
	s_nop 0
	v_cvt_pk_bf16_f32 v84, v234, v235
	v_cvt_pk_bf16_f32 v85, v236, v237
	v_cvt_pk_bf16_f32 v86, v238, v239
	v_cvt_pk_bf16_f32 v87, v240, v241
	ds_write_b128 v228, v[84:87]
	ds_read_b128 v[80:83], v229
	v_pk_mul_f32 v[234:235], v[76:77], v[230:231]
	v_pk_mul_f32 v[236:237], v[78:79], v[230:231]
	v_pk_mul_f32 v[238:239], v[72:73], v[230:231]
	v_pk_mul_f32 v[240:241], v[74:75], v[230:231]
	v_exp_f32_e32 v234, v234
	v_exp_f32_e32 v235, v235
	v_exp_f32_e32 v236, v236
	v_exp_f32_e32 v237, v237
	v_exp_f32_e32 v238, v238
	v_exp_f32_e32 v239, v239
	v_exp_f32_e32 v240, v240
	v_exp_f32_e32 v241, v241
	v_pk_add_f32 v[234:235], v[234:235], v[232:233]
	v_pk_add_f32 v[236:237], v[236:237], v[232:233]
	v_pk_add_f32 v[238:239], v[238:239], v[232:233]
	v_pk_add_f32 v[240:241], v[240:241], v[232:233]
	v_rcp_f32_e32 v234, v234
	v_rcp_f32_e32 v235, v235
	v_rcp_f32_e32 v236, v236
	v_rcp_f32_e32 v237, v237
	v_rcp_f32_e32 v238, v238
	v_rcp_f32_e32 v239, v239
	v_rcp_f32_e32 v240, v240
	v_rcp_f32_e32 v241, v241
	s_nop 0
	v_cvt_pk_bf16_f32 v76, v234, v235
	v_cvt_pk_bf16_f32 v77, v236, v237
	v_cvt_pk_bf16_f32 v78, v238, v239
	v_cvt_pk_bf16_f32 v79, v240, v241
	ds_write_b128 v228, v[76:79]
	ds_read_b128 v[72:75], v229
	v_pk_mul_f32 v[234:235], v[68:69], v[230:231]
	v_pk_mul_f32 v[236:237], v[70:71], v[230:231]
	v_pk_mul_f32 v[238:239], v[64:65], v[230:231]
	v_pk_mul_f32 v[240:241], v[66:67], v[230:231]
	v_exp_f32_e32 v234, v234
	v_exp_f32_e32 v235, v235
	v_exp_f32_e32 v236, v236
	v_exp_f32_e32 v237, v237
	v_exp_f32_e32 v238, v238
	v_exp_f32_e32 v239, v239
	v_exp_f32_e32 v240, v240
	v_exp_f32_e32 v241, v241
	v_pk_add_f32 v[234:235], v[234:235], v[232:233]
	v_pk_add_f32 v[236:237], v[236:237], v[232:233]
	v_pk_add_f32 v[238:239], v[238:239], v[232:233]
	v_pk_add_f32 v[240:241], v[240:241], v[232:233]
	v_rcp_f32_e32 v234, v234
	v_rcp_f32_e32 v235, v235
	v_rcp_f32_e32 v236, v236
	v_rcp_f32_e32 v237, v237
	v_rcp_f32_e32 v238, v238
	v_rcp_f32_e32 v239, v239
	v_rcp_f32_e32 v240, v240
	v_rcp_f32_e32 v241, v241
	s_nop 0
	v_cvt_pk_bf16_f32 v68, v234, v235
	v_cvt_pk_bf16_f32 v69, v236, v237
	v_cvt_pk_bf16_f32 v70, v238, v239
	v_cvt_pk_bf16_f32 v71, v240, v241
	ds_write_b128 v228, v[68:71]
	ds_read_b128 v[64:67], v229
	v_pk_mov_b32 v[92:93], 0, 0
	v_pk_mov_b32 v[94:95], 0, 0
	v_pk_mov_b32 v[84:85], 0, 0
	v_pk_mov_b32 v[86:87], 0, 0
	v_pk_mov_b32 v[76:77], 0, 0
	v_pk_mov_b32 v[78:79], 0, 0
	v_pk_mov_b32 v[68:69], 0, 0
	v_pk_mov_b32 v[70:71], 0, 0
	v_add_u32_e32 v160, s100, v160
	s_waitcnt lgkmcnt(6)
	global_store_dwordx4 v160, v[88:91], s[98:99] nt
	s_waitcnt lgkmcnt(4)
	global_store_dwordx4 v160, v[80:83], s[98:99] offset:256 nt
	v_add_u32_e32 v160, s100, v160
	s_waitcnt lgkmcnt(2)
	global_store_dwordx4 v160, v[72:75], s[98:99] nt
	s_waitcnt lgkmcnt(0)
; __device__ __forceinline__ u32x4 pack8(const float (&f)[8]) { u32x4 w; w.x = cvt_pk_bf16(f[0], f[1]); w.y = cvt_pk_bf16(f[2], f[3]); w.z = cvt_pk_bf16(f[4], f[5]); w.w = cvt_pk_bf16(f[6], f[7]); return w; }
; __device__ __forceinline__ float sigm(float x) { return __builtin_amdgcn_rcpf(1.f + __builtin_amdgcn_exp2f(-1.4426950408889634f * x)); }
;     __device__ __forceinline__ void operator()(const f32x4 (&acc)[2][2][4][2], const Unit& u, int wr, int wc, int fr, int fq) const {
;     ...
;             for (int m = 0; m < 4; ++m) { bf16_t* rowp = base + (size_t)(row0 + ai * HALF + m * 16) * ldc + col0;
; #pragma unroll
;                 for (int bj = 0; bj < 2; ++bj) { const f32x4 v0 = acc[ai][bj][m][0], v1 = acc[ai][bj][m][1];
;                     float f[8] = {v0[0], v0[1], v0[2], v0[3], v1[0], v1[1], v1[2], v1[3]};
;                     if (act == 1) {
; #pragma unroll
;                         for (int e = 0; e < 8; ++e) f[e] = sigm(f[e]);
;                     } else if (act == 2) {
; #pragma unroll
;                         for (int e = 0; e < 8; ++e) f[e] = f[e] * sigm(f[e]);
;                     }
;                     __builtin_nontemporal_store(pack8(f), (u32x4*)(rowp + bj * HALF)); } }
	global_store_dwordx4 v160, v[64:67], s[98:99] offset:256 nt
	v_pk_mov_b32 v[88:89], 0, 0
	v_pk_mov_b32 v[90:91], 0, 0
	v_pk_mov_b32 v[80:81], 0, 0
	v_pk_mov_b32 v[82:83], 0, 0
	v_pk_mov_b32 v[72:73], 0, 0
	v_pk_mov_b32 v[74:75], 0, 0
	v_pk_mov_b32 v[64:65], 0, 0
	v_pk_mov_b32 v[66:67], 0, 0
	v_pk_mul_f32 v[234:235], v[60:61], v[230:231]
	v_pk_mul_f32 v[236:237], v[62:63], v[230:231]
	v_pk_mul_f32 v[238:239], v[56:57], v[230:231]
	v_pk_mul_f32 v[240:241], v[58:59], v[230:231]
	v_exp_f32_e32 v234, v234
	v_exp_f32_e32 v235, v235
	v_exp_f32_e32 v236, v236
	v_exp_f32_e32 v237, v237
	v_exp_f32_e32 v238, v238
	v_exp_f32_e32 v239, v239
	v_exp_f32_e32 v240, v240
	v_exp_f32_e32 v241, v241
	v_pk_add_f32 v[234:235], v[234:235], v[232:233]
	v_pk_add_f32 v[236:237], v[236:237], v[232:233]
	v_pk_add_f32 v[238:239], v[238:239], v[232:233]
	v_pk_add_f32 v[240:241], v[240:241], v[232:233]
	v_rcp_f32_e32 v234, v234
	v_rcp_f32_e32 v235, v235
	v_rcp_f32_e32 v236, v236
	v_rcp_f32_e32 v237, v237
	v_rcp_f32_e32 v238, v238
	v_rcp_f32_e32 v239, v239
	v_rcp_f32_e32 v240, v240
	v_rcp_f32_e32 v241, v241
	s_nop 0
	v_cvt_pk_bf16_f32 v60, v234, v235
	v_cvt_pk_bf16_f32 v61, v236, v237
	v_cvt_pk_bf16_f32 v62, v238, v239
	v_cvt_pk_bf16_f32 v63, v240, v241
	ds_write_b128 v228, v[60:63]
	ds_read_b128 v[56:59], v229
	v_pk_mul_f32 v[234:235], v[52:53], v[230:231]
	v_pk_mul_f32 v[236:237], v[54:55], v[230:231]
	v_pk_mul_f32 v[238:239], v[48:49], v[230:231]
	v_pk_mul_f32 v[240:241], v[50:51], v[230:231]
	v_exp_f32_e32 v234, v234
	v_exp_f32_e32 v235, v235
	v_exp_f32_e32 v236, v236
	v_exp_f32_e32 v237, v237
	v_exp_f32_e32 v238, v238
	v_exp_f32_e32 v239, v239
	v_exp_f32_e32 v240, v240
	v_exp_f32_e32 v241, v241
	v_pk_add_f32 v[234:235], v[234:235], v[232:233]
	v_pk_add_f32 v[236:237], v[236:237], v[232:233]
	v_pk_add_f32 v[238:239], v[238:239], v[232:233]
	v_pk_add_f32 v[240:241], v[240:241], v[232:233]
	v_rcp_f32_e32 v234, v234
	v_rcp_f32_e32 v235, v235
	v_rcp_f32_e32 v236, v236
	v_rcp_f32_e32 v237, v237
	v_rcp_f32_e32 v238, v238
	v_rcp_f32_e32 v239, v239
	v_rcp_f32_e32 v240, v240
	v_rcp_f32_e32 v241, v241
	s_nop 0
	v_cvt_pk_bf16_f32 v52, v234, v235
	v_cvt_pk_bf16_f32 v53, v236, v237
	v_cvt_pk_bf16_f32 v54, v238, v239
	v_cvt_pk_bf16_f32 v55, v240, v241
	ds_write_b128 v228, v[52:55]
	ds_read_b128 v[48:51], v229
	v_pk_mul_f32 v[234:235], v[44:45], v[230:231]
	v_pk_mul_f32 v[236:237], v[46:47], v[230:231]
	v_pk_mul_f32 v[238:239], v[40:41], v[230:231]
	v_pk_mul_f32 v[240:241], v[42:43], v[230:231]
	v_exp_f32_e32 v234, v234
	v_exp_f32_e32 v235, v235
	v_exp_f32_e32 v236, v236
	v_exp_f32_e32 v237, v237
	v_exp_f32_e32 v238, v238
	v_exp_f32_e32 v239, v239
	v_exp_f32_e32 v240, v240
	v_exp_f32_e32 v241, v241
	v_pk_add_f32 v[234:235], v[234:235], v[232:233]
	v_pk_add_f32 v[236:237], v[236:237], v[232:233]
	v_pk_add_f32 v[238:239], v[238:239], v[232:233]
	v_pk_add_f32 v[240:241], v[240:241], v[232:233]
	v_rcp_f32_e32 v234, v234
	v_rcp_f32_e32 v235, v235
	v_rcp_f32_e32 v236, v236
	v_rcp_f32_e32 v237, v237
	v_rcp_f32_e32 v238, v238
	v_rcp_f32_e32 v239, v239
	v_rcp_f32_e32 v240, v240
	v_rcp_f32_e32 v241, v241
	s_nop 0
	v_cvt_pk_bf16_f32 v44, v234, v235
	v_cvt_pk_bf16_f32 v45, v236, v237
	v_cvt_pk_bf16_f32 v46, v238, v239
	v_cvt_pk_bf16_f32 v47, v240, v241
	ds_write_b128 v228, v[44:47]
	ds_read_b128 v[40:43], v229
	v_pk_mul_f32 v[234:235], v[36:37], v[230:231]
	v_pk_mul_f32 v[236:237], v[38:39], v[230:231]
	v_pk_mul_f32 v[238:239], v[32:33], v[230:231]
	v_pk_mul_f32 v[240:241], v[34:35], v[230:231]
	v_exp_f32_e32 v234, v234
	v_exp_f32_e32 v235, v235
	v_exp_f32_e32 v236, v236
	v_exp_f32_e32 v237, v237
	v_exp_f32_e32 v238, v238
	v_exp_f32_e32 v239, v239
	v_exp_f32_e32 v240, v240
	v_exp_f32_e32 v241, v241
	v_pk_add_f32 v[234:235], v[234:235], v[232:233]
	v_pk_add_f32 v[236:237], v[236:237], v[232:233]
	v_pk_add_f32 v[238:239], v[238:239], v[232:233]
	v_pk_add_f32 v[240:241], v[240:241], v[232:233]
	v_rcp_f32_e32 v234, v234
	v_rcp_f32_e32 v235, v235
	v_rcp_f32_e32 v236, v236
	v_rcp_f32_e32 v237, v237
	v_rcp_f32_e32 v238, v238
	v_rcp_f32_e32 v239, v239
	v_rcp_f32_e32 v240, v240
	v_rcp_f32_e32 v241, v241
	s_nop 0
	v_cvt_pk_bf16_f32 v36, v234, v235
	v_cvt_pk_bf16_f32 v37, v236, v237
	v_cvt_pk_bf16_f32 v38, v238, v239
	v_cvt_pk_bf16_f32 v39, v240, v241
	ds_write_b128 v228, v[36:39]
	ds_read_b128 v[32:35], v229
	v_pk_mov_b32 v[60:61], 0, 0
	v_pk_mov_b32 v[62:63], 0, 0
	v_pk_mov_b32 v[52:53], 0, 0
	v_pk_mov_b32 v[54:55], 0, 0
	v_pk_mov_b32 v[44:45], 0, 0
	v_pk_mov_b32 v[46:47], 0, 0
	v_pk_mov_b32 v[36:37], 0, 0
	v_pk_mov_b32 v[38:39], 0, 0
	v_mad_u32_u24 v160, s100, 5, v160
	s_waitcnt lgkmcnt(6)
	global_store_dwordx4 v160, v[56:59], s[98:99] nt
	s_waitcnt lgkmcnt(4)
	global_store_dwordx4 v160, v[48:51], s[98:99] offset:256 nt
	v_add_u32_e32 v160, s100, v160
	s_waitcnt lgkmcnt(2)
	global_store_dwordx4 v160, v[40:43], s[98:99] nt
	s_waitcnt lgkmcnt(0)
; __device__ __forceinline__ u32x4 pack8(const float (&f)[8]) { u32x4 w; w.x = cvt_pk_bf16(f[0], f[1]); w.y = cvt_pk_bf16(f[2], f[3]); w.z = cvt_pk_bf16(f[4], f[5]); w.w = cvt_pk_bf16(f[6], f[7]); return w; }
; __device__ __forceinline__ float sigm(float x) { return __builtin_amdgcn_rcpf(1.f + __builtin_amdgcn_exp2f(-1.4426950408889634f * x)); }
;     __device__ __forceinline__ void operator()(const f32x4 (&acc)[2][2][4][2], const Unit& u, int wr, int wc, int fr, int fq) const {
;     ...
;             for (int m = 0; m < 4; ++m) { bf16_t* rowp = base + (size_t)(row0 + ai * HALF + m * 16) * ldc + col0;
; #pragma unroll
;                 for (int bj = 0; bj < 2; ++bj) { const f32x4 v0 = acc[ai][bj][m][0], v1 = acc[ai][bj][m][1];
;                     float f[8] = {v0[0], v0[1], v0[2], v0[3], v1[0], v1[1], v1[2], v1[3]};
;                     if (act == 1) {
; #pragma unroll
;                         for (int e = 0; e < 8; ++e) f[e] = sigm(f[e]);
;                     } else if (act == 2) {
; #pragma unroll
;                         for (int e = 0; e < 8; ++e) f[e] = f[e] * sigm(f[e]);
;                     }
;                     __builtin_nontemporal_store(pack8(f), (u32x4*)(rowp + bj * HALF)); } }
	global_store_dwordx4 v160, v[32:35], s[98:99] offset:256 nt
	v_pk_mov_b32 v[56:57], 0, 0
	v_pk_mov_b32 v[58:59], 0, 0
	v_pk_mov_b32 v[48:49], 0, 0
	v_pk_mov_b32 v[50:51], 0, 0
	v_pk_mov_b32 v[40:41], 0, 0
	v_pk_mov_b32 v[42:43], 0, 0
	v_pk_mov_b32 v[32:33], 0, 0
	v_pk_mov_b32 v[34:35], 0, 0
	v_pk_mul_f32 v[234:235], v[28:29], v[230:231]
	v_pk_mul_f32 v[236:237], v[30:31], v[230:231]
	v_pk_mul_f32 v[238:239], v[24:25], v[230:231]
	v_pk_mul_f32 v[240:241], v[26:27], v[230:231]
	v_exp_f32_e32 v234, v234
	v_exp_f32_e32 v235, v235
	v_exp_f32_e32 v236, v236
	v_exp_f32_e32 v237, v237
	v_exp_f32_e32 v238, v238
	v_exp_f32_e32 v239, v239
	v_exp_f32_e32 v240, v240
	v_exp_f32_e32 v241, v241
	v_pk_add_f32 v[234:235], v[234:235], v[232:233]
	v_pk_add_f32 v[236:237], v[236:237], v[232:233]
	v_pk_add_f32 v[238:239], v[238:239], v[232:233]
	v_pk_add_f32 v[240:241], v[240:241], v[232:233]
	v_rcp_f32_e32 v234, v234
	v_rcp_f32_e32 v235, v235
	v_rcp_f32_e32 v236, v236
	v_rcp_f32_e32 v237, v237
	v_rcp_f32_e32 v238, v238
	v_rcp_f32_e32 v239, v239
	v_rcp_f32_e32 v240, v240
	v_rcp_f32_e32 v241, v241
	s_nop 0
	v_cvt_pk_bf16_f32 v28, v234, v235
	v_cvt_pk_bf16_f32 v29, v236, v237
	v_cvt_pk_bf16_f32 v30, v238, v239
	v_cvt_pk_bf16_f32 v31, v240, v241
	ds_write_b128 v228, v[28:31]
	ds_read_b128 v[24:27], v229
	v_pk_mul_f32 v[234:235], v[20:21], v[230:231]
	v_pk_mul_f32 v[236:237], v[22:23], v[230:231]
	v_pk_mul_f32 v[238:239], v[16:17], v[230:231]
	v_pk_mul_f32 v[240:241], v[18:19], v[230:231]
	v_exp_f32_e32 v234, v234
	v_exp_f32_e32 v235, v235
	v_exp_f32_e32 v236, v236
	v_exp_f32_e32 v237, v237
	v_exp_f32_e32 v238, v238
	v_exp_f32_e32 v239, v239
	v_exp_f32_e32 v240, v240
	v_exp_f32_e32 v241, v241
	v_pk_add_f32 v[234:235], v[234:235], v[232:233]
	v_pk_add_f32 v[236:237], v[236:237], v[232:233]
	v_pk_add_f32 v[238:239], v[238:239], v[232:233]
	v_pk_add_f32 v[240:241], v[240:241], v[232:233]
	v_rcp_f32_e32 v234, v234
	v_rcp_f32_e32 v235, v235
	v_rcp_f32_e32 v236, v236
	v_rcp_f32_e32 v237, v237
	v_rcp_f32_e32 v238, v238
	v_rcp_f32_e32 v239, v239
	v_rcp_f32_e32 v240, v240
	v_rcp_f32_e32 v241, v241
	s_nop 0
	v_cvt_pk_bf16_f32 v20, v234, v235
	v_cvt_pk_bf16_f32 v21, v236, v237
	v_cvt_pk_bf16_f32 v22, v238, v239
	v_cvt_pk_bf16_f32 v23, v240, v241
	ds_write_b128 v228, v[20:23]
	ds_read_b128 v[16:19], v229
	v_pk_mul_f32 v[234:235], v[12:13], v[230:231]
	v_pk_mul_f32 v[236:237], v[14:15], v[230:231]
	v_pk_mul_f32 v[238:239], v[8:9], v[230:231]
	v_pk_mul_f32 v[240:241], v[10:11], v[230:231]
	v_exp_f32_e32 v234, v234
	v_exp_f32_e32 v235, v235
	v_exp_f32_e32 v236, v236
	v_exp_f32_e32 v237, v237
	v_exp_f32_e32 v238, v238
	v_exp_f32_e32 v239, v239
	v_exp_f32_e32 v240, v240
	v_exp_f32_e32 v241, v241
	v_pk_add_f32 v[234:235], v[234:235], v[232:233]
	v_pk_add_f32 v[236:237], v[236:237], v[232:233]
	v_pk_add_f32 v[238:239], v[238:239], v[232:233]
	v_pk_add_f32 v[240:241], v[240:241], v[232:233]
	v_rcp_f32_e32 v234, v234
	v_rcp_f32_e32 v235, v235
	v_rcp_f32_e32 v236, v236
	v_rcp_f32_e32 v237, v237
	v_rcp_f32_e32 v238, v238
	v_rcp_f32_e32 v239, v239
	v_rcp_f32_e32 v240, v240
	v_rcp_f32_e32 v241, v241
	s_nop 0
	v_cvt_pk_bf16_f32 v12, v234, v235
	v_cvt_pk_bf16_f32 v13, v236, v237
	v_cvt_pk_bf16_f32 v14, v238, v239
	v_cvt_pk_bf16_f32 v15, v240, v241
	ds_write_b128 v228, v[12:15]
	ds_read_b128 v[8:11], v229
	v_pk_mul_f32 v[234:235], v[4:5], v[230:231]
	v_pk_mul_f32 v[236:237], v[6:7], v[230:231]
	v_pk_mul_f32 v[238:239], v[0:1], v[230:231]
	v_pk_mul_f32 v[240:241], v[2:3], v[230:231]
	v_exp_f32_e32 v234, v234
	v_exp_f32_e32 v235, v235
	v_exp_f32_e32 v236, v236
	v_exp_f32_e32 v237, v237
	v_exp_f32_e32 v238, v238
	v_exp_f32_e32 v239, v239
	v_exp_f32_e32 v240, v240
	v_exp_f32_e32 v241, v241
	v_pk_add_f32 v[234:235], v[234:235], v[232:233]
	v_pk_add_f32 v[236:237], v[236:237], v[232:233]
	v_pk_add_f32 v[238:239], v[238:239], v[232:233]
	v_pk_add_f32 v[240:241], v[240:241], v[232:233]
	v_rcp_f32_e32 v234, v234
	v_rcp_f32_e32 v235, v235
	v_rcp_f32_e32 v236, v236
	v_rcp_f32_e32 v237, v237
	v_rcp_f32_e32 v238, v238
	v_rcp_f32_e32 v239, v239
	v_rcp_f32_e32 v240, v240
	v_rcp_f32_e32 v241, v241
	s_nop 0
	v_cvt_pk_bf16_f32 v4, v234, v235
	v_cvt_pk_bf16_f32 v5, v236, v237
	v_cvt_pk_bf16_f32 v6, v238, v239
	v_cvt_pk_bf16_f32 v7, v240, v241
	ds_write_b128 v228, v[4:7]
	ds_read_b128 v[0:3], v229
	v_pk_mov_b32 v[28:29], 0, 0
	v_pk_mov_b32 v[30:31], 0, 0
	v_pk_mov_b32 v[20:21], 0, 0
	v_pk_mov_b32 v[22:23], 0, 0
	v_pk_mov_b32 v[12:13], 0, 0
	v_pk_mov_b32 v[14:15], 0, 0
	v_pk_mov_b32 v[4:5], 0, 0
	v_pk_mov_b32 v[6:7], 0, 0
	v_add_u32_e32 v160, s100, v160
	s_waitcnt lgkmcnt(6)
	global_store_dwordx4 v160, v[24:27], s[98:99] nt
	s_waitcnt lgkmcnt(4)
	global_store_dwordx4 v160, v[16:19], s[98:99] offset:256 nt
	v_add_u32_e32 v160, s100, v160
	s_waitcnt lgkmcnt(2)
	global_store_dwordx4 v160, v[8:11], s[98:99] nt
	s_waitcnt lgkmcnt(0)
	global_store_dwordx4 v160, v[0:3], s[98:99] offset:256 nt
	v_pk_mov_b32 v[24:25], 0, 0
	v_pk_mov_b32 v[26:27], 0, 0
	v_pk_mov_b32 v[16:17], 0, 0
	v_pk_mov_b32 v[18:19], 0, 0
	v_pk_mov_b32 v[8:9], 0, 0
	v_pk_mov_b32 v[10:11], 0, 0
	v_pk_mov_b32 v[0:1], 0, 0
	v_pk_mov_b32 v[2:3], 0, 0
	s_andn2_b64 vcc, exec, s[0:1]
	s_mov_b64 s[0:1], -1
	s_branch .Lp1_tail

;     __host__ __device__ bool next(int i, Unit& u) const { Unit v; if (!base.next(i >> 1, v)) return false; u.pm = v.pm + ((i & 1) ? 128 : 0); u.pn = v.pn + ((i & 1) ? 4 : 0); return true; }
; #define PG8_STAGE(bufoff, gbase, voff) do { _Pragma("unroll") for (int _i = 0; _i < 2; ++_i) \
;         __builtin_amdgcn_global_load_lds((const unsigned*)((const char*)(gbase) + (voff)[_i]), (PG8_LAS unsigned*)(lds + (bufoff) + ldsw + _i * 8192), 16, 0, 0); } while (0)
; #define PG8_LDA(dst, b, h) do { _Pragma("unroll") for (int m = 0; m < 4; ++m) _Pragma("unroll") for (int k = 0; k < 2; ++k) dst[m][k] = *(const PG8_LAS bf16x8*)(lds + PG8_SA(b, h) + aoff + m * 2048 + k * 1024); } while (0)
; #define PG8_WAIT_V(n) asm volatile("s_waitcnt vmcnt(" #n ")" ::: "memory")
; #define PG8_WAIT_L(n) asm volatile("s_waitcnt lgkmcnt(" #n ")" ::: "memory")
; template <class Epi, class Sched, bool ALIGN_EPI = false, bool SP2 = false>
; __device__ __forceinline__ void gemm_phase(PG8_LAS unsigned char* lds, const Gemm g, const Sched& S, const Epi& E) {
;     ...
;         const bool has_next = S.next(ui + 1, nxt);
;         const char* nA = has_next ? (const char*)g.A + (size_t)nxt.pm * tstep : cA; const char* nB = has_next ? (const char*)g.Bt + (size_t)nxt.pn * tstep : cB;
;         for (int t = 0; t < nt; t += 2) {
;             const bool last = (t == nt - 2);
;             const char* a1 = cA + (size_t)(t + 1) * kstep;
;             const char* a2 = last ? nA : cA + (size_t)(t + 2) * kstep; const char* b2 = last ? nB : cB + (size_t)(t + 2) * kstep;
;             const char* a3 = a2 + kstep; const char* b3 = b2 + kstep;
;             if (last && has_next) S.a_ready(nxt);
;             if constexpr (SP2) {
;             PG8_LDB(B0, 0, 0); PG8_LDB(B1, 0, 1); PG8_SCHED; PG8_LDA(At, 0, 0); PG8_STAGE(PG8_SA(1, 1), a1 + hstep, voffA);
;             PG8_WAIT_V(8); PG8_WAIT_L(0); PG8_BAR; PG8_MMA(0, 0, At, B0); PG8_MMA(0, 1, At, B1); PG8_BAR; PG8_SCHED;
;             PG8_LDA(At, 0, 1); PG8_STAGE(PG8_SB(0, 0), b2, voffB); PG8_STAGE(PG8_SB(0, 1), b2 + hstep, voffB); PG8_STAGE(PG8_SA(0, 0), a2, voffA);
;     ...
; #pragma unroll
;         for (int a = 0; a < 2; ++a)
; #pragma unroll
;             for (int b = 0; b < 2; ++b)
; #pragma unroll
;                 for (int m = 0; m < 4; ++m)
; #pragma unroll
;                     for (int n = 0; n < 2; ++n) acc[a][b][m][n] = (f32x4){0.f, 0.f, 0.f, 0.f};
.LBB0_736:
	s_ashr_i32 s25, s24, 31
	s_lshl_b64 s[26:27], s[24:25], 19
	s_add_u32 s26, s8, s26
	s_addc_u32 s27, s9, s27
	s_and_b64 s[38:39], s[4:5], exec
	s_cselect_b32 s25, s27, s43
	s_cselect_b32 s56, s26, s42
	s_ashr_i32 s23, s22, 31
	s_lshl_b64 s[38:39], s[22:23], 19
	s_add_u32 s38, s76, s38
	s_addc_u32 s39, s77, s39
	s_and_b64 s[46:47], s[4:5], exec
	s_cselect_b32 s23, s39, s45
	s_cselect_b32 s57, s38, s44
	s_add_u32 s42, s42, 0x40080
	s_addc_u32 s43, s43, 0
	s_add_u32 s58, s44, 0x100
	v_mov_b32_e32 v0, 0
	s_addc_u32 s59, s45, 0
	s_mov_b32 s60, -2
	s_cmp_lg_u32 s98, 0
	s_cbranch_scc1 .Lskipz_p5
	v_mov_b32_e32 v1, v0
	v_mov_b32_e32 v2, v0
	v_mov_b32_e32 v3, v0
	v_mov_b32_e32 v4, v0
	v_mov_b32_e32 v5, v0
	v_mov_b32_e32 v6, v0
	v_mov_b32_e32 v7, v0
	v_mov_b32_e32 v16, v0
	v_mov_b32_e32 v17, v0
	v_mov_b32_e32 v18, v0
	v_mov_b32_e32 v19, v0
	v_mov_b32_e32 v20, v0
	v_mov_b32_e32 v21, v0
	v_mov_b32_e32 v22, v0
	v_mov_b32_e32 v23, v0
	v_mov_b32_e32 v32, v0
	v_mov_b32_e32 v33, v0
	v_mov_b32_e32 v34, v0
	v_mov_b32_e32 v35, v0
	v_mov_b32_e32 v36, v0
	v_mov_b32_e32 v37, v0
	v_mov_b32_e32 v38, v0
	v_mov_b32_e32 v39, v0
	v_mov_b32_e32 v48, v0
	v_mov_b32_e32 v49, v0
	v_mov_b32_e32 v50, v0
	v_mov_b32_e32 v51, v0
	v_mov_b32_e32 v52, v0
	v_mov_b32_e32 v53, v0
	v_mov_b32_e32 v54, v0
	v_mov_b32_e32 v55, v0
	v_mov_b32_e32 v8, v0
	v_mov_b32_e32 v9, v0
	v_mov_b32_e32 v10, v0
	v_mov_b32_e32 v11, v0
	v_mov_b32_e32 v12, v0
	v_mov_b32_e32 v13, v0
	v_mov_b32_e32 v14, v0
	v_mov_b32_e32 v15, v0
	v_mov_b32_e32 v24, v0
	v_mov_b32_e32 v25, v0
	v_mov_b32_e32 v26, v0
	v_mov_b32_e32 v27, v0
	v_mov_b32_e32 v28, v0
	v_mov_b32_e32 v29, v0
	v_mov_b32_e32 v30, v0
	v_mov_b32_e32 v31, v0
	v_mov_b32_e32 v40, v0
	v_mov_b32_e32 v41, v0
	v_mov_b32_e32 v42, v0
	v_mov_b32_e32 v43, v0
	v_mov_b32_e32 v44, v0
	v_mov_b32_e32 v45, v0
	v_mov_b32_e32 v46, v0
	v_mov_b32_e32 v47, v0
	v_mov_b32_e32 v56, v0
	v_mov_b32_e32 v57, v0
	v_mov_b32_e32 v58, v0
	v_mov_b32_e32 v59, v0
	v_mov_b32_e32 v60, v0
	v_mov_b32_e32 v61, v0
	v_mov_b32_e32 v62, v0
	v_mov_b32_e32 v63, v0
	v_mov_b32_e32 v64, v0
	v_mov_b32_e32 v65, v0
	v_mov_b32_e32 v66, v0
	v_mov_b32_e32 v67, v0
	v_mov_b32_e32 v68, v0
	v_mov_b32_e32 v69, v0
	v_mov_b32_e32 v70, v0
	v_mov_b32_e32 v71, v0
	v_mov_b32_e32 v80, v0
	v_mov_b32_e32 v81, v0
	v_mov_b32_e32 v82, v0
	v_mov_b32_e32 v83, v0
	v_mov_b32_e32 v84, v0
	v_mov_b32_e32 v85, v0
	v_mov_b32_e32 v86, v0
	v_mov_b32_e32 v87, v0
	v_mov_b32_e32 v96, v0
	v_mov_b32_e32 v97, v0
	v_mov_b32_e32 v98, v0
	v_mov_b32_e32 v99, v0
	v_mov_b32_e32 v100, v0
	v_mov_b32_e32 v101, v0
	v_mov_b32_e32 v102, v0
	v_mov_b32_e32 v103, v0
	v_mov_b32_e32 v112, v0
	v_mov_b32_e32 v113, v0
	v_mov_b32_e32 v114, v0
	v_mov_b32_e32 v115, v0
	v_mov_b32_e32 v116, v0
	v_mov_b32_e32 v117, v0
	v_mov_b32_e32 v118, v0
	v_mov_b32_e32 v119, v0
	v_mov_b32_e32 v72, v0
	v_mov_b32_e32 v73, v0
	v_mov_b32_e32 v74, v0
	v_mov_b32_e32 v75, v0
	v_mov_b32_e32 v76, v0
	v_mov_b32_e32 v77, v0
	v_mov_b32_e32 v78, v0
	v_mov_b32_e32 v79, v0
	v_mov_b32_e32 v88, v0
	v_mov_b32_e32 v89, v0
	v_mov_b32_e32 v90, v0
	v_mov_b32_e32 v91, v0
	v_mov_b32_e32 v92, v0
	v_mov_b32_e32 v93, v0
	v_mov_b32_e32 v94, v0
	v_mov_b32_e32 v95, v0
	v_mov_b32_e32 v104, v0
	v_mov_b32_e32 v105, v0
	v_mov_b32_e32 v106, v0
	v_mov_b32_e32 v107, v0
	v_mov_b32_e32 v108, v0
	v_mov_b32_e32 v109, v0
	v_mov_b32_e32 v110, v0
	v_mov_b32_e32 v111, v0
	v_mov_b32_e32 v120, v0
	v_mov_b32_e32 v121, v0
	v_mov_b32_e32 v122, v0
	v_mov_b32_e32 v123, v0
	v_mov_b32_e32 v124, v0
	v_mov_b32_e32 v125, v0
	v_mov_b32_e32 v126, v0
	v_mov_b32_e32 v127, v0
.Lskipz_p5:
.LBB0_737:
	ds_read_b128 v[144:147], v155
	ds_read_b128 v[148:151], v155 offset:1024
	ds_read_b128 v[160:163], v155 offset:2048
	ds_read_b128 v[164:167], v155 offset:3072
	ds_read_b128 v[168:171], v156
	ds_read_b128 v[172:175], v156 offset:1024
	ds_read_b128 v[176:179], v156 offset:2048
	ds_read_b128 v[180:183], v156 offset:3072
	s_add_u32 s44, s42, 0xfffc0080
	s_addc_u32 s45, s43, -1
	s_cmp_eq_u32 s60, 12
	s_cselect_b32 s47, s25, s45
	s_cselect_b32 s46, s56, s44
	s_cselect_b32 s45, s23, s59
	s_cselect_b32 s44, s57, s58
	v_lshl_add_u64 v[218:219], s[42:43], 0, v[136:137]
	s_add_i32 m0, s28, 0xc000
	ds_read_b128 v[184:187], v157
	ds_read_b128 v[188:191], v157 offset:1024
	ds_read_b128 v[192:195], v157 offset:2048
	ds_read_b128 v[196:199], v157 offset:3072
	ds_read_b128 v[200:203], v157 offset:4096
	ds_read_b128 v[206:209], v157 offset:5120
	ds_read_b128 v[210:213], v157 offset:6144
	ds_read_b128 v[214:217], v157 offset:7168
	s_cmp_lg_u32 s98, 0
	s_cbranch_scc1 .Lgr_p5_alt1
	global_load_lds_dwordx4 v[218:219], off
	v_lshl_add_u64 v[218:219], s[42:43], 0, v[138:139]
	s_add_i32 m0, s28, 0xe000
	s_nop 0
	global_load_lds_dwordx4 v[218:219], off
	s_waitcnt vmcnt(8)
	s_branch .Lgr_p5_join1

; __device__ __forceinline__ u32x4 pack8(const float (&f)[8]) { u32x4 w; w.x = cvt_pk_bf16(f[0], f[1]); w.y = cvt_pk_bf16(f[2], f[3]); w.z = cvt_pk_bf16(f[4], f[5]); w.w = cvt_pk_bf16(f[6], f[7]); return w; }
;     __device__ __forceinline__ void operator()(const f32x4 (&acc)[2][2][4][2], const Unit& u, int wr, int wc, int fr, int fq) const {
;         const int row0 = u.pm * BM + wr * 64 + fr, col0 = u.pn * BM + wc * 32 + 8 * fq;
; #pragma unroll
;         for (int ai = 0; ai < 2; ++ai)
; #pragma unroll
;             for (int m = 0; m < 4; ++m) { const int row = row0 + ai * HALF + m * 16; const float rs = __builtin_amdgcn_rsqf(ssq[row] * (1.0f / 1024.0f) + 1e-6f); bf16_t* rowp = U + (size_t)row * 4096 + col0;
; #pragma unroll
;                 for (int bj = 0; bj < 2; ++bj) { const f32x4 v0 = acc[ai][bj][m][0], v1 = acc[ai][bj][m][1];
;                     float f[8] = {v0[0], v0[1], v0[2], v0[3], v1[0], v1[1], v1[2], v1[3]};
; #pragma unroll
;                     for (int e = 0; e < 8; ++e) { const float r = fmaxf(f[e] * rs, 0.f); f[e] = r * r; }
;                     *(u32x4*)(rowp + bj * HALF) = pack8(f); } }
.LBB0_740:
	s_add_u32 s100, s56, 0x40080
	s_addc_u32 s101, s25, 0
	v_lshl_add_u64 v[218:219], s[100:101], 0, v[136:137]
	s_add_i32 m0, s28, 0xc000
	s_nop 0
	global_load_lds_dwordx4 v[218:219], off
	v_lshl_add_u64 v[218:219], s[100:101], 0, v[138:139]
	s_add_i32 m0, s28, 0xe000
	s_nop 0
	global_load_lds_dwordx4 v[218:219], off
	s_mov_b32 s98, 1
	v_lshl_add_u32 v148, s40, 8, v152
	v_lshlrev_b32_e32 v150, 2, v148
	global_load_dword v228, v150, s[68:69]
	global_load_dword v230, v150, s[68:69] offset:64
	global_load_dword v232, v150, s[68:69] offset:128
	global_load_dword v234, v150, s[68:69] offset:192
	global_load_dword v236, v150, s[68:69] offset:512
	global_load_dword v238, v150, s[68:69] offset:576
	global_load_dword v240, v150, s[68:69] offset:640
	global_load_dword v242, v150, s[68:69] offset:704
	v_bfe_u32 v144, v204, 2, 4
	v_and_or_b32 v149, v152, -16, v144
	v_and_b32_e32 v144, 3, v204
	v_lshlrev_b32_e32 v144, 3, v144
	v_and_b32_e32 v146, 0xffffffe7, v154
	v_or_b32_e32 v146, v146, v144
	v_lshl_add_u32 v149, s40, 8, v149
	v_lshl_or_b32 v146, s55, 8, v146
	v_lshlrev_b32_e32 v146, 1, v146
	v_lshl_add_u32 v151, v149, 13, v146
	v_lshrrev_b32_e32 v144, 6, v204
	v_mul_u32_u24_e32 v144, 0x500, v144
	v_add_u32_e32 v144, 0x20000, v144
	v_and_b32_e32 v244, 15, v204
	v_mul_u32_u24_e32 v244, 0x50, v244
	v_bfe_u32 v145, v204, 4, 2
	v_lshl_add_u32 v244, v145, 4, v244
	v_add_u32_e32 v244, v244, v144
	v_bfe_u32 v245, v204, 2, 4
	v_mul_u32_u24_e32 v245, 0x50, v245
	v_and_b32_e32 v145, 3, v204
	v_lshl_add_u32 v245, v145, 4, v245
	v_add_u32_e32 v245, v245, v144
	s_waitcnt vmcnt(0)
	v_fmamk_f32 v228, v228, 0x3a800000, v158
	v_fmamk_f32 v230, v230, 0x3a800000, v158
	v_fmamk_f32 v232, v232, 0x3a800000, v158
	v_fmamk_f32 v234, v234, 0x3a800000, v158
	v_fmamk_f32 v236, v236, 0x3a800000, v158
	v_fmamk_f32 v238, v238, 0x3a800000, v158
	v_fmamk_f32 v240, v240, 0x3a800000, v158
	v_fmamk_f32 v242, v242, 0x3a800000, v158
	v_rsq_f32_e32 v228, v228
	v_rsq_f32_e32 v230, v230
	v_rsq_f32_e32 v232, v232
	v_rsq_f32_e32 v234, v234
	v_rsq_f32_e32 v236, v236
	v_rsq_f32_e32 v238, v238
	v_rsq_f32_e32 v240, v240
	v_rsq_f32_e32 v242, v242
	s_nop 0
	v_pk_mul_f32 v[124:125], v[124:125], v[228:229] op_sel_hi:[1,0]
	v_pk_mul_f32 v[126:127], v[126:127], v[228:229] op_sel_hi:[1,0]
	v_pk_mul_f32 v[120:121], v[120:121], v[228:229] op_sel_hi:[1,0]
	v_pk_mul_f32 v[122:123], v[122:123], v[228:229] op_sel_hi:[1,0]
	v_max_f32_e32 v124, 0, v124
	v_max_f32_e32 v125, 0, v125
	v_max_f32_e32 v126, 0, v126
	v_max_f32_e32 v127, 0, v127
	v_max_f32_e32 v120, 0, v120
	v_max_f32_e32 v121, 0, v121
	v_max_f32_e32 v122, 0, v122
	v_max_f32_e32 v123, 0, v123
	v_pk_mul_f32 v[124:125], v[124:125], v[124:125]
	v_pk_mul_f32 v[126:127], v[126:127], v[126:127]
	v_pk_mul_f32 v[120:121], v[120:121], v[120:121]
	v_pk_mul_f32 v[122:123], v[122:123], v[122:123]
	v_cvt_pk_bf16_f32 v124, v124, v125
	v_cvt_pk_bf16_f32 v125, v126, v127
	v_cvt_pk_bf16_f32 v126, v120, v121
	v_cvt_pk_bf16_f32 v127, v122, v123
	ds_write_b128 v244, v[124:127]
	ds_read_b128 v[120:123], v245
	v_pk_mul_f32 v[116:117], v[116:117], v[228:229] op_sel_hi:[1,0]
	v_pk_mul_f32 v[118:119], v[118:119], v[228:229] op_sel_hi:[1,0]
	v_pk_mul_f32 v[112:113], v[112:113], v[228:229] op_sel_hi:[1,0]
	v_pk_mul_f32 v[114:115], v[114:115], v[228:229] op_sel_hi:[1,0]
	v_max_f32_e32 v116, 0, v116
	v_max_f32_e32 v117, 0, v117
	v_max_f32_e32 v118, 0, v118
	v_max_f32_e32 v119, 0, v119
	v_max_f32_e32 v112, 0, v112
	v_max_f32_e32 v113, 0, v113
	v_max_f32_e32 v114, 0, v114
	v_max_f32_e32 v115, 0, v115
	v_pk_mul_f32 v[116:117], v[116:117], v[116:117]
	v_pk_mul_f32 v[118:119], v[118:119], v[118:119]
	v_pk_mul_f32 v[112:113], v[112:113], v[112:113]
	v_pk_mul_f32 v[114:115], v[114:115], v[114:115]
	v_cvt_pk_bf16_f32 v116, v116, v117
	v_cvt_pk_bf16_f32 v117, v118, v119
	v_cvt_pk_bf16_f32 v118, v112, v113
	v_cvt_pk_bf16_f32 v119, v114, v115
	ds_write_b128 v244, v[116:119]
	ds_read_b128 v[112:115], v245
	v_pk_mul_f32 v[108:109], v[108:109], v[230:231] op_sel_hi:[1,0]
	v_pk_mul_f32 v[110:111], v[110:111], v[230:231] op_sel_hi:[1,0]
	v_pk_mul_f32 v[104:105], v[104:105], v[230:231] op_sel_hi:[1,0]
	v_pk_mul_f32 v[106:107], v[106:107], v[230:231] op_sel_hi:[1,0]
	v_max_f32_e32 v108, 0, v108
	v_max_f32_e32 v109, 0, v109
	v_max_f32_e32 v110, 0, v110
	v_max_f32_e32 v111, 0, v111
	v_max_f32_e32 v104, 0, v104
	v_max_f32_e32 v105, 0, v105
	v_max_f32_e32 v106, 0, v106
	v_max_f32_e32 v107, 0, v107
	v_pk_mul_f32 v[108:109], v[108:109], v[108:109]
	v_pk_mul_f32 v[110:111], v[110:111], v[110:111]
	v_pk_mul_f32 v[104:105], v[104:105], v[104:105]
	v_pk_mul_f32 v[106:107], v[106:107], v[106:107]
	v_cvt_pk_bf16_f32 v108, v108, v109
	v_cvt_pk_bf16_f32 v109, v110, v111
	v_cvt_pk_bf16_f32 v110, v104, v105
	v_cvt_pk_bf16_f32 v111, v106, v107
	ds_write_b128 v244, v[108:111]
	ds_read_b128 v[104:107], v245
	v_pk_mul_f32 v[100:101], v[100:101], v[230:231] op_sel_hi:[1,0]
	v_pk_mul_f32 v[102:103], v[102:103], v[230:231] op_sel_hi:[1,0]
	v_pk_mul_f32 v[96:97], v[96:97], v[230:231] op_sel_hi:[1,0]
	v_pk_mul_f32 v[98:99], v[98:99], v[230:231] op_sel_hi:[1,0]
	v_max_f32_e32 v100, 0, v100
	v_max_f32_e32 v101, 0, v101
	v_max_f32_e32 v102, 0, v102
	v_max_f32_e32 v103, 0, v103
	v_max_f32_e32 v96, 0, v96
	v_max_f32_e32 v97, 0, v97
	v_max_f32_e32 v98, 0, v98
	v_max_f32_e32 v99, 0, v99
	v_pk_mul_f32 v[100:101], v[100:101], v[100:101]
	v_pk_mul_f32 v[102:103], v[102:103], v[102:103]
	v_pk_mul_f32 v[96:97], v[96:97], v[96:97]
	v_pk_mul_f32 v[98:99], v[98:99], v[98:99]
	v_cvt_pk_bf16_f32 v100, v100, v101
	v_cvt_pk_bf16_f32 v101, v102, v103
	v_cvt_pk_bf16_f32 v102, v96, v97
	v_cvt_pk_bf16_f32 v103, v98, v99
	ds_write_b128 v244, v[100:103]
	ds_read_b128 v[96:99], v245
	v_pk_mov_b32 v[124:125], 0, 0
	v_pk_mov_b32 v[126:127], 0, 0
	v_pk_mov_b32 v[116:117], 0, 0
	v_pk_mov_b32 v[118:119], 0, 0
	v_pk_mov_b32 v[108:109], 0, 0
	v_pk_mov_b32 v[110:111], 0, 0
	v_pk_mov_b32 v[100:101], 0, 0
	v_pk_mov_b32 v[102:103], 0, 0
	s_waitcnt lgkmcnt(6)
; __device__ __forceinline__ u32x4 pack8(const float (&f)[8]) { u32x4 w; w.x = cvt_pk_bf16(f[0], f[1]); w.y = cvt_pk_bf16(f[2], f[3]); w.z = cvt_pk_bf16(f[4], f[5]); w.w = cvt_pk_bf16(f[6], f[7]); return w; }
;     __device__ __forceinline__ void operator()(const f32x4 (&acc)[2][2][4][2], const Unit& u, int wr, int wc, int fr, int fq) const {
;         const int row0 = u.pm * BM + wr * 64 + fr, col0 = u.pn * BM + wc * 32 + 8 * fq;
; #pragma unroll
;         for (int ai = 0; ai < 2; ++ai)
; #pragma unroll
;             for (int m = 0; m < 4; ++m) { const int row = row0 + ai * HALF + m * 16; const float rs = __builtin_amdgcn_rsqf(ssq[row] * (1.0f / 1024.0f) + 1e-6f); bf16_t* rowp = U + (size_t)row * 4096 + col0;
; #pragma unroll
;                 for (int bj = 0; bj < 2; ++bj) { const f32x4 v0 = acc[ai][bj][m][0], v1 = acc[ai][bj][m][1];
;                     float f[8] = {v0[0], v0[1], v0[2], v0[3], v1[0], v1[1], v1[2], v1[3]};
; #pragma unroll
;                     for (int e = 0; e < 8; ++e) { const float r = fmaxf(f[e] * rs, 0.f); f[e] = r * r; }
;                     *(u32x4*)(rowp + bj * HALF) = pack8(f); } }
	global_store_dwordx4 v151, v[120:123], s[36:37]
	s_waitcnt lgkmcnt(4)
	global_store_dwordx4 v151, v[112:115], s[36:37] offset:256
	v_add_u32_e32 v151, 0x20000, v151
	s_waitcnt lgkmcnt(2)
	global_store_dwordx4 v151, v[104:107], s[36:37]
	s_waitcnt lgkmcnt(0)
	global_store_dwordx4 v151, v[96:99], s[36:37] offset:256
	v_pk_mov_b32 v[120:121], 0, 0
	v_pk_mov_b32 v[122:123], 0, 0
	v_pk_mov_b32 v[112:113], 0, 0
	v_pk_mov_b32 v[114:115], 0, 0
	v_pk_mov_b32 v[104:105], 0, 0
	v_pk_mov_b32 v[106:107], 0, 0
	v_pk_mov_b32 v[96:97], 0, 0
	v_pk_mov_b32 v[98:99], 0, 0
	v_pk_mul_f32 v[92:93], v[92:93], v[232:233] op_sel_hi:[1,0]
	v_pk_mul_f32 v[94:95], v[94:95], v[232:233] op_sel_hi:[1,0]
	v_pk_mul_f32 v[88:89], v[88:89], v[232:233] op_sel_hi:[1,0]
	v_pk_mul_f32 v[90:91], v[90:91], v[232:233] op_sel_hi:[1,0]
	v_max_f32_e32 v92, 0, v92
	v_max_f32_e32 v93, 0, v93
	v_max_f32_e32 v94, 0, v94
	v_max_f32_e32 v95, 0, v95
	v_max_f32_e32 v88, 0, v88
	v_max_f32_e32 v89, 0, v89
	v_max_f32_e32 v90, 0, v90
	v_max_f32_e32 v91, 0, v91
	v_pk_mul_f32 v[92:93], v[92:93], v[92:93]
	v_pk_mul_f32 v[94:95], v[94:95], v[94:95]
	v_pk_mul_f32 v[88:89], v[88:89], v[88:89]
	v_pk_mul_f32 v[90:91], v[90:91], v[90:91]
	v_cvt_pk_bf16_f32 v92, v92, v93
	v_cvt_pk_bf16_f32 v93, v94, v95
	v_cvt_pk_bf16_f32 v94, v88, v89
	v_cvt_pk_bf16_f32 v95, v90, v91
	ds_write_b128 v244, v[92:95]
	ds_read_b128 v[88:91], v245
	v_pk_mul_f32 v[84:85], v[84:85], v[232:233] op_sel_hi:[1,0]
	v_pk_mul_f32 v[86:87], v[86:87], v[232:233] op_sel_hi:[1,0]
	v_pk_mul_f32 v[80:81], v[80:81], v[232:233] op_sel_hi:[1,0]
	v_pk_mul_f32 v[82:83], v[82:83], v[232:233] op_sel_hi:[1,0]
	v_max_f32_e32 v84, 0, v84
	v_max_f32_e32 v85, 0, v85
	v_max_f32_e32 v86, 0, v86
	v_max_f32_e32 v87, 0, v87
	v_max_f32_e32 v80, 0, v80
	v_max_f32_e32 v81, 0, v81
	v_max_f32_e32 v82, 0, v82
	v_max_f32_e32 v83, 0, v83
	v_pk_mul_f32 v[84:85], v[84:85], v[84:85]
	v_pk_mul_f32 v[86:87], v[86:87], v[86:87]
	v_pk_mul_f32 v[80:81], v[80:81], v[80:81]
	v_pk_mul_f32 v[82:83], v[82:83], v[82:83]
	v_cvt_pk_bf16_f32 v84, v84, v85
	v_cvt_pk_bf16_f32 v85, v86, v87
	v_cvt_pk_bf16_f32 v86, v80, v81
	v_cvt_pk_bf16_f32 v87, v82, v83
	ds_write_b128 v244, v[84:87]
	ds_read_b128 v[80:83], v245
	v_pk_mul_f32 v[76:77], v[76:77], v[234:235] op_sel_hi:[1,0]
	v_pk_mul_f32 v[78:79], v[78:79], v[234:235] op_sel_hi:[1,0]
	v_pk_mul_f32 v[72:73], v[72:73], v[234:235] op_sel_hi:[1,0]
	v_pk_mul_f32 v[74:75], v[74:75], v[234:235] op_sel_hi:[1,0]
	v_max_f32_e32 v76, 0, v76
	v_max_f32_e32 v77, 0, v77
	v_max_f32_e32 v78, 0, v78
	v_max_f32_e32 v79, 0, v79
	v_max_f32_e32 v72, 0, v72
	v_max_f32_e32 v73, 0, v73
	v_max_f32_e32 v74, 0, v74
	v_max_f32_e32 v75, 0, v75
	v_pk_mul_f32 v[76:77], v[76:77], v[76:77]
	v_pk_mul_f32 v[78:79], v[78:79], v[78:79]
	v_pk_mul_f32 v[72:73], v[72:73], v[72:73]
	v_pk_mul_f32 v[74:75], v[74:75], v[74:75]
	v_cvt_pk_bf16_f32 v76, v76, v77
	v_cvt_pk_bf16_f32 v77, v78, v79
	v_cvt_pk_bf16_f32 v78, v72, v73
	v_cvt_pk_bf16_f32 v79, v74, v75
	ds_write_b128 v244, v[76:79]
	ds_read_b128 v[72:75], v245
	v_pk_mul_f32 v[68:69], v[68:69], v[234:235] op_sel_hi:[1,0]
	v_pk_mul_f32 v[70:71], v[70:71], v[234:235] op_sel_hi:[1,0]
	v_pk_mul_f32 v[64:65], v[64:65], v[234:235] op_sel_hi:[1,0]
	v_pk_mul_f32 v[66:67], v[66:67], v[234:235] op_sel_hi:[1,0]
	v_max_f32_e32 v68, 0, v68
	v_max_f32_e32 v69, 0, v69
	v_max_f32_e32 v70, 0, v70
	v_max_f32_e32 v71, 0, v71
	v_max_f32_e32 v64, 0, v64
	v_max_f32_e32 v65, 0, v65
	v_max_f32_e32 v66, 0, v66
	v_max_f32_e32 v67, 0, v67
	v_pk_mul_f32 v[68:69], v[68:69], v[68:69]
	v_pk_mul_f32 v[70:71], v[70:71], v[70:71]
	v_pk_mul_f32 v[64:65], v[64:65], v[64:65]
	v_pk_mul_f32 v[66:67], v[66:67], v[66:67]
	v_cvt_pk_bf16_f32 v68, v68, v69
	v_cvt_pk_bf16_f32 v69, v70, v71
	v_cvt_pk_bf16_f32 v70, v64, v65
	v_cvt_pk_bf16_f32 v71, v66, v67
	ds_write_b128 v244, v[68:71]
	ds_read_b128 v[64:67], v245
	v_pk_mov_b32 v[92:93], 0, 0
	v_pk_mov_b32 v[94:95], 0, 0
	v_pk_mov_b32 v[84:85], 0, 0
	v_pk_mov_b32 v[86:87], 0, 0
	v_pk_mov_b32 v[76:77], 0, 0
	v_pk_mov_b32 v[78:79], 0, 0
	v_pk_mov_b32 v[68:69], 0, 0
	v_pk_mov_b32 v[70:71], 0, 0
	v_add_u32_e32 v151, 0x20000, v151
	s_waitcnt lgkmcnt(6)
	global_store_dwordx4 v151, v[88:91], s[36:37]
	s_waitcnt lgkmcnt(4)
	global_store_dwordx4 v151, v[80:83], s[36:37] offset:256
	v_add_u32_e32 v151, 0x20000, v151
	s_waitcnt lgkmcnt(2)
	global_store_dwordx4 v151, v[72:75], s[36:37]
	s_waitcnt lgkmcnt(0)
; __device__ __forceinline__ u32x4 pack8(const float (&f)[8]) { u32x4 w; w.x = cvt_pk_bf16(f[0], f[1]); w.y = cvt_pk_bf16(f[2], f[3]); w.z = cvt_pk_bf16(f[4], f[5]); w.w = cvt_pk_bf16(f[6], f[7]); return w; }
;     __device__ __forceinline__ void operator()(const f32x4 (&acc)[2][2][4][2], const Unit& u, int wr, int wc, int fr, int fq) const {
;         const int row0 = u.pm * BM + wr * 64 + fr, col0 = u.pn * BM + wc * 32 + 8 * fq;
; #pragma unroll
;         for (int ai = 0; ai < 2; ++ai)
; #pragma unroll
;             for (int m = 0; m < 4; ++m) { const int row = row0 + ai * HALF + m * 16; const float rs = __builtin_amdgcn_rsqf(ssq[row] * (1.0f / 1024.0f) + 1e-6f); bf16_t* rowp = U + (size_t)row * 4096 + col0;
; #pragma unroll
;                 for (int bj = 0; bj < 2; ++bj) { const f32x4 v0 = acc[ai][bj][m][0], v1 = acc[ai][bj][m][1];
;                     float f[8] = {v0[0], v0[1], v0[2], v0[3], v1[0], v1[1], v1[2], v1[3]};
; #pragma unroll
;                     for (int e = 0; e < 8; ++e) { const float r = fmaxf(f[e] * rs, 0.f); f[e] = r * r; }
;                     *(u32x4*)(rowp + bj * HALF) = pack8(f); } }
	global_store_dwordx4 v151, v[64:67], s[36:37] offset:256
	v_pk_mov_b32 v[88:89], 0, 0
	v_pk_mov_b32 v[90:91], 0, 0
	v_pk_mov_b32 v[80:81], 0, 0
	v_pk_mov_b32 v[82:83], 0, 0
	v_pk_mov_b32 v[72:73], 0, 0
	v_pk_mov_b32 v[74:75], 0, 0
	v_pk_mov_b32 v[64:65], 0, 0
	v_pk_mov_b32 v[66:67], 0, 0
	v_pk_mul_f32 v[60:61], v[60:61], v[236:237] op_sel_hi:[1,0]
	v_pk_mul_f32 v[62:63], v[62:63], v[236:237] op_sel_hi:[1,0]
	v_pk_mul_f32 v[56:57], v[56:57], v[236:237] op_sel_hi:[1,0]
	v_pk_mul_f32 v[58:59], v[58:59], v[236:237] op_sel_hi:[1,0]
	v_max_f32_e32 v60, 0, v60
	v_max_f32_e32 v61, 0, v61
	v_max_f32_e32 v62, 0, v62
	v_max_f32_e32 v63, 0, v63
	v_max_f32_e32 v56, 0, v56
	v_max_f32_e32 v57, 0, v57
	v_max_f32_e32 v58, 0, v58
	v_max_f32_e32 v59, 0, v59
	v_pk_mul_f32 v[60:61], v[60:61], v[60:61]
	v_pk_mul_f32 v[62:63], v[62:63], v[62:63]
	v_pk_mul_f32 v[56:57], v[56:57], v[56:57]
	v_pk_mul_f32 v[58:59], v[58:59], v[58:59]
	v_cvt_pk_bf16_f32 v60, v60, v61
	v_cvt_pk_bf16_f32 v61, v62, v63
	v_cvt_pk_bf16_f32 v62, v56, v57
	v_cvt_pk_bf16_f32 v63, v58, v59
	ds_write_b128 v244, v[60:63]
	ds_read_b128 v[56:59], v245
	v_pk_mul_f32 v[52:53], v[52:53], v[236:237] op_sel_hi:[1,0]
	v_pk_mul_f32 v[54:55], v[54:55], v[236:237] op_sel_hi:[1,0]
	v_pk_mul_f32 v[48:49], v[48:49], v[236:237] op_sel_hi:[1,0]
	v_pk_mul_f32 v[50:51], v[50:51], v[236:237] op_sel_hi:[1,0]
	v_max_f32_e32 v52, 0, v52
	v_max_f32_e32 v53, 0, v53
	v_max_f32_e32 v54, 0, v54
	v_max_f32_e32 v55, 0, v55
	v_max_f32_e32 v48, 0, v48
	v_max_f32_e32 v49, 0, v49
	v_max_f32_e32 v50, 0, v50
	v_max_f32_e32 v51, 0, v51
	v_pk_mul_f32 v[52:53], v[52:53], v[52:53]
	v_pk_mul_f32 v[54:55], v[54:55], v[54:55]
	v_pk_mul_f32 v[48:49], v[48:49], v[48:49]
	v_pk_mul_f32 v[50:51], v[50:51], v[50:51]
	v_cvt_pk_bf16_f32 v52, v52, v53
	v_cvt_pk_bf16_f32 v53, v54, v55
	v_cvt_pk_bf16_f32 v54, v48, v49
	v_cvt_pk_bf16_f32 v55, v50, v51
	ds_write_b128 v244, v[52:55]
	ds_read_b128 v[48:51], v245
	v_pk_mul_f32 v[44:45], v[44:45], v[238:239] op_sel_hi:[1,0]
	v_pk_mul_f32 v[46:47], v[46:47], v[238:239] op_sel_hi:[1,0]
	v_pk_mul_f32 v[40:41], v[40:41], v[238:239] op_sel_hi:[1,0]
	v_pk_mul_f32 v[42:43], v[42:43], v[238:239] op_sel_hi:[1,0]
	v_max_f32_e32 v44, 0, v44
	v_max_f32_e32 v45, 0, v45
	v_max_f32_e32 v46, 0, v46
	v_max_f32_e32 v47, 0, v47
	v_max_f32_e32 v40, 0, v40
	v_max_f32_e32 v41, 0, v41
	v_max_f32_e32 v42, 0, v42
	v_max_f32_e32 v43, 0, v43
	v_pk_mul_f32 v[44:45], v[44:45], v[44:45]
	v_pk_mul_f32 v[46:47], v[46:47], v[46:47]
	v_pk_mul_f32 v[40:41], v[40:41], v[40:41]
	v_pk_mul_f32 v[42:43], v[42:43], v[42:43]
	v_cvt_pk_bf16_f32 v44, v44, v45
	v_cvt_pk_bf16_f32 v45, v46, v47
	v_cvt_pk_bf16_f32 v46, v40, v41
	v_cvt_pk_bf16_f32 v47, v42, v43
	ds_write_b128 v244, v[44:47]
	ds_read_b128 v[40:43], v245
	v_pk_mul_f32 v[36:37], v[36:37], v[238:239] op_sel_hi:[1,0]
	v_pk_mul_f32 v[38:39], v[38:39], v[238:239] op_sel_hi:[1,0]
	v_pk_mul_f32 v[32:33], v[32:33], v[238:239] op_sel_hi:[1,0]
	v_pk_mul_f32 v[34:35], v[34:35], v[238:239] op_sel_hi:[1,0]
	v_max_f32_e32 v36, 0, v36
	v_max_f32_e32 v37, 0, v37
	v_max_f32_e32 v38, 0, v38
	v_max_f32_e32 v39, 0, v39
	v_max_f32_e32 v32, 0, v32
	v_max_f32_e32 v33, 0, v33
	v_max_f32_e32 v34, 0, v34
	v_max_f32_e32 v35, 0, v35
	v_pk_mul_f32 v[36:37], v[36:37], v[36:37]
	v_pk_mul_f32 v[38:39], v[38:39], v[38:39]
	v_pk_mul_f32 v[32:33], v[32:33], v[32:33]
	v_pk_mul_f32 v[34:35], v[34:35], v[34:35]
	v_cvt_pk_bf16_f32 v36, v36, v37
	v_cvt_pk_bf16_f32 v37, v38, v39
	v_cvt_pk_bf16_f32 v38, v32, v33
	v_cvt_pk_bf16_f32 v39, v34, v35
	ds_write_b128 v244, v[36:39]
	ds_read_b128 v[32:35], v245
	v_pk_mov_b32 v[60:61], 0, 0
	v_pk_mov_b32 v[62:63], 0, 0
	v_pk_mov_b32 v[52:53], 0, 0
	v_pk_mov_b32 v[54:55], 0, 0
	v_pk_mov_b32 v[44:45], 0, 0
	v_pk_mov_b32 v[46:47], 0, 0
	v_pk_mov_b32 v[36:37], 0, 0
	v_pk_mov_b32 v[38:39], 0, 0
	v_add_u32_e32 v151, 0xa0000, v151
	s_waitcnt lgkmcnt(6)
	global_store_dwordx4 v151, v[56:59], s[36:37]
	s_waitcnt lgkmcnt(4)
	global_store_dwordx4 v151, v[48:51], s[36:37] offset:256
	v_add_u32_e32 v151, 0x20000, v151
	s_waitcnt lgkmcnt(2)
	global_store_dwordx4 v151, v[40:43], s[36:37]
	s_waitcnt lgkmcnt(0)
; __device__ __forceinline__ u32x4 pack8(const float (&f)[8]) { u32x4 w; w.x = cvt_pk_bf16(f[0], f[1]); w.y = cvt_pk_bf16(f[2], f[3]); w.z = cvt_pk_bf16(f[4], f[5]); w.w = cvt_pk_bf16(f[6], f[7]); return w; }
;     __device__ __forceinline__ void operator()(const f32x4 (&acc)[2][2][4][2], const Unit& u, int wr, int wc, int fr, int fq) const {
;         const int row0 = u.pm * BM + wr * 64 + fr, col0 = u.pn * BM + wc * 32 + 8 * fq;
; #pragma unroll
;         for (int ai = 0; ai < 2; ++ai)
; #pragma unroll
;             for (int m = 0; m < 4; ++m) { const int row = row0 + ai * HALF + m * 16; const float rs = __builtin_amdgcn_rsqf(ssq[row] * (1.0f / 1024.0f) + 1e-6f); bf16_t* rowp = U + (size_t)row * 4096 + col0;
; #pragma unroll
;                 for (int bj = 0; bj < 2; ++bj) { const f32x4 v0 = acc[ai][bj][m][0], v1 = acc[ai][bj][m][1];
;                     float f[8] = {v0[0], v0[1], v0[2], v0[3], v1[0], v1[1], v1[2], v1[3]};
; #pragma unroll
;                     for (int e = 0; e < 8; ++e) { const float r = fmaxf(f[e] * rs, 0.f); f[e] = r * r; }
;                     *(u32x4*)(rowp + bj * HALF) = pack8(f); } }
	global_store_dwordx4 v151, v[32:35], s[36:37] offset:256
	v_pk_mov_b32 v[56:57], 0, 0
	v_pk_mov_b32 v[58:59], 0, 0
	v_pk_mov_b32 v[48:49], 0, 0
	v_pk_mov_b32 v[50:51], 0, 0
	v_pk_mov_b32 v[40:41], 0, 0
	v_pk_mov_b32 v[42:43], 0, 0
	v_pk_mov_b32 v[32:33], 0, 0
	v_pk_mov_b32 v[34:35], 0, 0
	v_pk_mul_f32 v[28:29], v[28:29], v[240:241] op_sel_hi:[1,0]
	v_pk_mul_f32 v[30:31], v[30:31], v[240:241] op_sel_hi:[1,0]
	v_pk_mul_f32 v[24:25], v[24:25], v[240:241] op_sel_hi:[1,0]
	v_pk_mul_f32 v[26:27], v[26:27], v[240:241] op_sel_hi:[1,0]
	v_max_f32_e32 v28, 0, v28
	v_max_f32_e32 v29, 0, v29
	v_max_f32_e32 v30, 0, v30
	v_max_f32_e32 v31, 0, v31
	v_max_f32_e32 v24, 0, v24
	v_max_f32_e32 v25, 0, v25
	v_max_f32_e32 v26, 0, v26
	v_max_f32_e32 v27, 0, v27
	v_pk_mul_f32 v[28:29], v[28:29], v[28:29]
	v_pk_mul_f32 v[30:31], v[30:31], v[30:31]
	v_pk_mul_f32 v[24:25], v[24:25], v[24:25]
	v_pk_mul_f32 v[26:27], v[26:27], v[26:27]
	v_cvt_pk_bf16_f32 v28, v28, v29
	v_cvt_pk_bf16_f32 v29, v30, v31
	v_cvt_pk_bf16_f32 v30, v24, v25
	v_cvt_pk_bf16_f32 v31, v26, v27
	ds_write_b128 v244, v[28:31]
	ds_read_b128 v[24:27], v245
	v_pk_mul_f32 v[20:21], v[20:21], v[240:241] op_sel_hi:[1,0]
	v_pk_mul_f32 v[22:23], v[22:23], v[240:241] op_sel_hi:[1,0]
	v_pk_mul_f32 v[16:17], v[16:17], v[240:241] op_sel_hi:[1,0]
	v_pk_mul_f32 v[18:19], v[18:19], v[240:241] op_sel_hi:[1,0]
	v_max_f32_e32 v20, 0, v20
	v_max_f32_e32 v21, 0, v21
	v_max_f32_e32 v22, 0, v22
	v_max_f32_e32 v23, 0, v23
	v_max_f32_e32 v16, 0, v16
	v_max_f32_e32 v17, 0, v17
	v_max_f32_e32 v18, 0, v18
	v_max_f32_e32 v19, 0, v19
	v_pk_mul_f32 v[20:21], v[20:21], v[20:21]
	v_pk_mul_f32 v[22:23], v[22:23], v[22:23]
	v_pk_mul_f32 v[16:17], v[16:17], v[16:17]
	v_pk_mul_f32 v[18:19], v[18:19], v[18:19]
	v_cvt_pk_bf16_f32 v20, v20, v21
	v_cvt_pk_bf16_f32 v21, v22, v23
	v_cvt_pk_bf16_f32 v22, v16, v17
	v_cvt_pk_bf16_f32 v23, v18, v19
	ds_write_b128 v244, v[20:23]
	ds_read_b128 v[16:19], v245
	v_pk_mul_f32 v[12:13], v[12:13], v[242:243] op_sel_hi:[1,0]
	v_pk_mul_f32 v[14:15], v[14:15], v[242:243] op_sel_hi:[1,0]
	v_pk_mul_f32 v[8:9], v[8:9], v[242:243] op_sel_hi:[1,0]
	v_pk_mul_f32 v[10:11], v[10:11], v[242:243] op_sel_hi:[1,0]
	v_max_f32_e32 v12, 0, v12
	v_max_f32_e32 v13, 0, v13
	v_max_f32_e32 v14, 0, v14
	v_max_f32_e32 v15, 0, v15
	v_max_f32_e32 v8, 0, v8
	v_max_f32_e32 v9, 0, v9
	v_max_f32_e32 v10, 0, v10
	v_max_f32_e32 v11, 0, v11
	v_pk_mul_f32 v[12:13], v[12:13], v[12:13]
	v_pk_mul_f32 v[14:15], v[14:15], v[14:15]
	v_pk_mul_f32 v[8:9], v[8:9], v[8:9]
	v_pk_mul_f32 v[10:11], v[10:11], v[10:11]
	v_cvt_pk_bf16_f32 v12, v12, v13
	v_cvt_pk_bf16_f32 v13, v14, v15
	v_cvt_pk_bf16_f32 v14, v8, v9
	v_cvt_pk_bf16_f32 v15, v10, v11
	ds_write_b128 v244, v[12:15]
	ds_read_b128 v[8:11], v245
	v_pk_mul_f32 v[4:5], v[4:5], v[242:243] op_sel_hi:[1,0]
	v_pk_mul_f32 v[6:7], v[6:7], v[242:243] op_sel_hi:[1,0]
	v_pk_mul_f32 v[0:1], v[0:1], v[242:243] op_sel_hi:[1,0]
	v_pk_mul_f32 v[2:3], v[2:3], v[242:243] op_sel_hi:[1,0]
	v_max_f32_e32 v4, 0, v4
	v_max_f32_e32 v5, 0, v5
	v_max_f32_e32 v6, 0, v6
	v_max_f32_e32 v7, 0, v7
	v_max_f32_e32 v0, 0, v0
	v_max_f32_e32 v1, 0, v1
	v_max_f32_e32 v2, 0, v2
	v_max_f32_e32 v3, 0, v3
	v_pk_mul_f32 v[4:5], v[4:5], v[4:5]
	v_pk_mul_f32 v[6:7], v[6:7], v[6:7]
	v_pk_mul_f32 v[0:1], v[0:1], v[0:1]
	v_pk_mul_f32 v[2:3], v[2:3], v[2:3]
	v_cvt_pk_bf16_f32 v4, v4, v5
	v_cvt_pk_bf16_f32 v5, v6, v7
	v_cvt_pk_bf16_f32 v6, v0, v1
	v_cvt_pk_bf16_f32 v7, v2, v3
	ds_write_b128 v244, v[4:7]
	ds_read_b128 v[0:3], v245
	v_pk_mov_b32 v[28:29], 0, 0
	v_pk_mov_b32 v[30:31], 0, 0
	v_pk_mov_b32 v[20:21], 0, 0
	v_pk_mov_b32 v[22:23], 0, 0
	v_pk_mov_b32 v[12:13], 0, 0
	v_pk_mov_b32 v[14:15], 0, 0
	v_pk_mov_b32 v[4:5], 0, 0
	v_pk_mov_b32 v[6:7], 0, 0
	v_add_u32_e32 v151, 0x20000, v151
	s_waitcnt lgkmcnt(6)
	global_store_dwordx4 v151, v[24:27], s[36:37]
	s_waitcnt lgkmcnt(4)
	global_store_dwordx4 v151, v[16:19], s[36:37] offset:256
	v_add_u32_e32 v151, 0x20000, v151
	s_waitcnt lgkmcnt(2)
	global_store_dwordx4 v151, v[8:11], s[36:37]
	s_waitcnt lgkmcnt(0)
	global_store_dwordx4 v151, v[0:3], s[36:37] offset:256
	v_pk_mov_b32 v[24:25], 0, 0
	v_pk_mov_b32 v[26:27], 0, 0
	v_pk_mov_b32 v[16:17], 0, 0
	v_pk_mov_b32 v[18:19], 0, 0
	v_pk_mov_b32 v[8:9], 0, 0
	v_pk_mov_b32 v[10:11], 0, 0
	v_pk_mov_b32 v[0:1], 0, 0
	v_pk_mov_b32 v[2:3], 0, 0
	s_andn2_b64 vcc, exec, s[4:5]
	s_mov_b64 s[4:5], -1
	s_cbranch_vccnz .LBB0_729
	s_andn2_b64 vcc, exec, s[6:7]
	s_cbranch_vccnz .LBB0_728
	s_barrier
	s_branch .LBB0_728
